# attention local K/V: row-halves staged once per workgroup by LDS-DMA into a 3-slot LDS ring (static LDS +16KiB) and read by all 8 waves, instead of each wave loading its own fragments from L2
# speedup vs baseline: 1.0146x; 1.0085x over previous
; template <bool LOCAL>
; __device__ __forceinline__ void attn_unit(const bf16_t* Q, const bf16_t* KT, const bf16_t* VT, bf16_t* O, LAS unsigned char* lds, int b, int h, int r, int w, int tq, int lane) {
;     ...
;     float mx = -INFINITY;
; #pragma unroll
;     for (int i = 0; i < 2 * NP; ++i) mx = fmaxf(mx, fmaxf(fmaxf(s[i][0], s[i][1]), fmaxf(s[i][2], s[i][3])));
;     mx = fmaxf(mx, __shfl_xor(mx, 16)); mx = fmaxf(mx, __shfl_xor(mx, 32));
.LBB9_673:
	s_or_b64 exec, exec, s[34:35]
	v_max_f32_e32 v66, v126, v126
	v_max_f32_e32 v67, v134, v134
	v_max_f32_e32 v66, v67, v66
	v_max_f32_e32 v67, v123, v123
	v_max_f32_e32 v68, v129, v129
	v_max_f32_e32 v67, v68, v67
	v_max3_f32 v66, v133, v132, v66
	v_max3_f32 v67, v128, v127, v67
	v_max3_f32 v66, v66, s16, v67
	v_max_f32_e32 v67, v118, v118
	v_max_f32_e32 v68, v125, v125
	v_max_f32_e32 v67, v68, v67
	v_max_f32_e32 v68, v115, v115
	v_max_f32_e32 v69, v121, v121
	v_max_f32_e32 v68, v69, v68
	v_max3_f32 v67, v124, v122, v67
	v_max3_f32 v68, v120, v119, v68
	v_max3_f32 v66, v66, v67, v68
	v_max_f32_e32 v67, v110, v110
	v_max_f32_e32 v68, v117, v117
	v_max_f32_e32 v67, v68, v67
	v_max_f32_e32 v68, v113, v113
	v_max_f32_e32 v69, v135, v135
	v_max_f32_e32 v68, v69, v68
	v_max3_f32 v67, v116, v114, v67
	v_max3_f32 v68, v112, v111, v68
	v_max3_f32 v66, v66, v67, v68
	v_max_f32_e32 v67, v102, v102
	v_max_f32_e32 v68, v109, v109
	v_max_f32_e32 v67, v68, v67
	v_max_f32_e32 v68, v99, v99
	v_max_f32_e32 v69, v105, v105
	v_max_f32_e32 v68, v69, v68
	v_max3_f32 v67, v108, v107, v67
	v_max3_f32 v68, v104, v103, v68
	v_max3_f32 v66, v66, v67, v68
	v_max_f32_e32 v67, v94, v94
	v_max_f32_e32 v68, v101, v101
	v_max_f32_e32 v67, v68, v67
	v_max_f32_e32 v68, v91, v91
	v_max_f32_e32 v69, v97, v97
	v_max_f32_e32 v68, v69, v68
	v_max3_f32 v67, v100, v98, v67
	v_max3_f32 v68, v96, v95, v68
	v_max3_f32 v66, v66, v67, v68
	v_max_f32_e32 v67, v86, v86
	v_max_f32_e32 v68, v93, v93
	v_max_f32_e32 v67, v68, v67
	v_max_f32_e32 v68, v89, v89
	v_max_f32_e32 v69, v138, v138
	v_max_f32_e32 v68, v69, v68
	v_max3_f32 v67, v92, v90, v67
	v_max3_f32 v68, v88, v87, v68
	v_max3_f32 v66, v66, v67, v68
	v_max_f32_e32 v67, v139, v139
	v_max_f32_e32 v68, v141, v141
	v_max_f32_e32 v67, v68, v67
	v_max_f32_e32 v68, v197, v197
	v_max_f32_e32 v69, v199, v199
	v_max_f32_e32 v68, v69, v68
	v_max3_f32 v67, v137, v136, v67
	v_max3_f32 v68, v195, v140, v68
	v_max3_f32 v66, v66, v67, v68
	v_max_f32_e32 v67, v200, v200
	v_max_f32_e32 v68, v202, v202
	v_max_f32_e32 v67, v68, v67
	v_max_f32_e32 v68, v204, v204
	v_max_f32_e32 v69, v205, v205
	v_max_f32_e32 v68, v69, v68
	v_max3_f32 v67, v198, v196, v67
	v_max3_f32 v68, v203, v201, v68
	v_max3_f32 v66, v66, v67, v68
	v_max_f32_e32 v67, v5, v5
	v_max_f32_e32 v68, v4, v4
	v_max_f32_e32 v67, v68, v67
	v_max_f32_e32 v68, v13, v13
	v_max_f32_e32 v69, v12, v12
	v_max_f32_e32 v68, v69, v68
	v_max3_f32 v67, v2, v3, v67
	v_max3_f32 v68, v10, v11, v68
	v_max3_f32 v66, v66, v67, v68
	v_max_f32_e32 v67, v9, v9
	v_max_f32_e32 v68, v8, v8
	v_max_f32_e32 v67, v68, v67
	v_max_f32_e32 v68, v21, v21
	v_max_f32_e32 v69, v20, v20
	v_max_f32_e32 v68, v69, v68
	v_max3_f32 v67, v6, v7, v67
	v_max3_f32 v68, v18, v19, v68
	v_max3_f32 v66, v66, v67, v68
	v_max_f32_e32 v67, v17, v17
	v_max_f32_e32 v68, v16, v16
	v_max_f32_e32 v67, v68, v67
	v_max_f32_e32 v68, v29, v29
	v_max_f32_e32 v69, v28, v28
	v_max_f32_e32 v68, v69, v68
	v_max3_f32 v67, v14, v15, v67
	v_max3_f32 v68, v26, v27, v68
	v_max3_f32 v66, v66, v67, v68
	v_max_f32_e32 v67, v25, v25
	v_max_f32_e32 v68, v24, v24
	v_max_f32_e32 v67, v68, v67
	v_max_f32_e32 v68, v37, v37
	v_max_f32_e32 v69, v36, v36
	v_max_f32_e32 v68, v69, v68
	v_max3_f32 v67, v22, v23, v67
	v_max3_f32 v68, v34, v35, v68
	v_max3_f32 v66, v66, v67, v68
	v_max_f32_e32 v67, v33, v33
	v_max_f32_e32 v68, v32, v32
	v_max_f32_e32 v67, v68, v67
	v_max_f32_e32 v68, v45, v45
	v_max_f32_e32 v69, v44, v44
	v_max_f32_e32 v68, v69, v68
	v_max3_f32 v67, v30, v31, v67
	v_max3_f32 v68, v42, v43, v68
	v_max3_f32 v66, v66, v67, v68
	v_max_f32_e32 v67, v41, v41
	v_max_f32_e32 v68, v40, v40
	v_max_f32_e32 v67, v68, v67
	v_max_f32_e32 v68, v53, v53
	v_max_f32_e32 v69, v52, v52
	v_max_f32_e32 v68, v69, v68
	v_max3_f32 v67, v38, v39, v67
	v_max3_f32 v68, v50, v51, v68
	v_max3_f32 v66, v66, v67, v68
	v_max_f32_e32 v67, v49, v49
	v_max_f32_e32 v68, v48, v48
	v_max_f32_e32 v67, v68, v67
	v_max_f32_e32 v68, v61, v61
	v_max_f32_e32 v69, v60, v60
	v_max_f32_e32 v68, v69, v68
	v_max3_f32 v67, v46, v47, v67
	v_max3_f32 v68, v58, v59, v68
	v_max3_f32 v66, v66, v67, v68
	v_max_f32_e32 v67, v57, v57
	v_max_f32_e32 v68, v56, v56
	v_max_f32_e32 v67, v68, v67
	v_max_f32_e32 v68, v65, v65
	v_max_f32_e32 v69, v64, v64
	v_max_f32_e32 v68, v69, v68
	v_max3_f32 v67, v54, v55, v67
	v_max3_f32 v68, v62, v63, v68
	v_max3_f32 v66, v66, v67, v68
	ds_bpermute_b32 v67, v181, v66
	v_lshlrev_b64 v[130:131], 11, v[162:163]
	s_waitcnt lgkmcnt(0)
	v_max_f32_e32 v67, v67, v67
	v_max_f32_e32 v66, v66, v67
	ds_bpermute_b32 v67, v182, v66
	s_waitcnt lgkmcnt(0)
; __device__ __forceinline__ unsigned cvt_pk_bf16(float lo, float hi) { unsigned r; asm volatile("v_cvt_pk_bf16_f32 %0, %1, %2" : "=v"(r) : "v"(lo), "v"(hi)); return r; }
; __device__ __forceinline__ float fast_exp2(float x) { return __builtin_amdgcn_exp2f(x); }
; template <bool LOCAL>
; __device__ __forceinline__ void attn_unit(const bf16_t* Q, const bf16_t* KT, const bf16_t* VT, bf16_t* O, LAS unsigned char* lds, int b, int h, int r, int w, int tq, int lane) {
;     ...
;     float sum = 0.f; const float mxl = mx * 1.4426950408889634f;
;     bf16x8 pb[NP];
; #pragma unroll
;     for (int p = 0; p < NP; ++p) { float e[8];
; #pragma unroll
;         for (int f = 0; f < 2; ++f)
; #pragma unroll
;             for (int j = 0; j < 4; ++j) { e[4 * f + j] = fast_exp2(fmaf(s[2 * p + f][j], 1.4426950408889634f, -mxl)); sum += e[4 * f + j]; }
;         u32x4 pw; pw.x = cvt_pk_bf16(e[0], e[1]); pw.y = cvt_pk_bf16(e[2], e[3]); pw.z = cvt_pk_bf16(e[4], e[5]); pw.w = cvt_pk_bf16(e[6], e[7]);
;         pb[p] = __builtin_bit_cast(bf16x8, pw); }
	v_max_f32_e32 v67, v67, v67
	v_max_f32_e32 v66, v66, v67
	v_mul_f32_e32 v106, 0xbfb8aa3b, v66
	v_fmamk_f32 v66, v133, 0x3fb8aa3b, v106
	v_exp_f32_e32 v66, v66
	v_fmamk_f32 v68, v132, 0x3fb8aa3b, v106
	v_exp_f32_e32 v68, v68
	v_fmamk_f32 v69, v134, 0x3fb8aa3b, v106
	v_exp_f32_e32 v69, v69
	v_fmamk_f32 v70, v126, 0x3fb8aa3b, v106
	v_exp_f32_e32 v70, v70
	v_fmamk_f32 v71, v128, 0x3fb8aa3b, v106
	v_add_f32_e32 v67, 0, v66
	v_exp_f32_e32 v71, v71
	v_fmamk_f32 v72, v127, 0x3fb8aa3b, v106
	v_add_f32_e32 v67, v68, v67
	v_exp_f32_e32 v72, v72
	v_fmamk_f32 v73, v129, 0x3fb8aa3b, v106
	v_add_f32_e32 v67, v69, v67
	v_exp_f32_e32 v73, v73
	v_fmamk_f32 v74, v123, 0x3fb8aa3b, v106
	v_add_f32_e32 v67, v70, v67
	v_exp_f32_e32 v74, v74
	v_add_f32_e32 v67, v71, v67
	v_add_f32_e32 v67, v72, v67
	v_add_f32_e32 v67, v73, v67
	v_add_f32_e32 v75, v74, v67
	v_cvt_pk_bf16_f32 v66, v66, v68
	v_cvt_pk_bf16_f32 v67, v69, v70
	v_fmamk_f32 v70, v124, 0x3fb8aa3b, v106
	v_exp_f32_e32 v70, v70
	v_cvt_pk_bf16_f32 v68, v71, v72
	v_fmamk_f32 v72, v122, 0x3fb8aa3b, v106
	v_cvt_pk_bf16_f32 v69, v73, v74
	v_exp_f32_e32 v72, v72
	v_fmamk_f32 v73, v125, 0x3fb8aa3b, v106
	v_exp_f32_e32 v73, v73
	v_fmamk_f32 v74, v118, 0x3fb8aa3b, v106
	v_add_f32_e32 v71, v70, v75
	v_exp_f32_e32 v74, v74
	v_fmamk_f32 v75, v120, 0x3fb8aa3b, v106
	v_exp_f32_e32 v75, v75
	v_fmamk_f32 v76, v119, 0x3fb8aa3b, v106
	v_add_f32_e32 v71, v72, v71
	v_exp_f32_e32 v76, v76
	v_fmamk_f32 v77, v121, 0x3fb8aa3b, v106
	v_add_f32_e32 v71, v73, v71
	v_exp_f32_e32 v77, v77
	v_fmamk_f32 v78, v115, 0x3fb8aa3b, v106
	v_add_f32_e32 v71, v74, v71
	v_exp_f32_e32 v78, v78
	v_add_f32_e32 v71, v75, v71
	v_add_f32_e32 v71, v76, v71
	v_add_f32_e32 v71, v77, v71
	v_add_f32_e32 v79, v78, v71
	v_cvt_pk_bf16_f32 v70, v70, v72
	v_cvt_pk_bf16_f32 v71, v73, v74
	v_fmamk_f32 v74, v116, 0x3fb8aa3b, v106
	v_exp_f32_e32 v74, v74
	v_cvt_pk_bf16_f32 v72, v75, v76
	v_fmamk_f32 v76, v114, 0x3fb8aa3b, v106
	v_cvt_pk_bf16_f32 v73, v77, v78
	v_exp_f32_e32 v76, v76
	v_fmamk_f32 v77, v117, 0x3fb8aa3b, v106
	v_exp_f32_e32 v77, v77
	v_fmamk_f32 v78, v110, 0x3fb8aa3b, v106
	v_add_f32_e32 v75, v74, v79
	v_exp_f32_e32 v78, v78
	v_fmamk_f32 v79, v112, 0x3fb8aa3b, v106
	v_exp_f32_e32 v79, v79
	v_fmamk_f32 v80, v111, 0x3fb8aa3b, v106
	v_add_f32_e32 v75, v76, v75
	v_exp_f32_e32 v80, v80
	v_fmamk_f32 v81, v135, 0x3fb8aa3b, v106
	v_add_f32_e32 v75, v77, v75
	v_exp_f32_e32 v81, v81
	v_fmamk_f32 v82, v113, 0x3fb8aa3b, v106
	v_add_f32_e32 v75, v78, v75
	v_exp_f32_e32 v82, v82
	v_add_f32_e32 v75, v79, v75
	v_add_f32_e32 v75, v80, v75
	v_add_f32_e32 v75, v81, v75
	v_add_f32_e32 v83, v82, v75
	v_cvt_pk_bf16_f32 v74, v74, v76
	v_cvt_pk_bf16_f32 v75, v77, v78
	v_fmamk_f32 v78, v108, 0x3fb8aa3b, v106
	v_exp_f32_e32 v78, v78
	v_cvt_pk_bf16_f32 v76, v79, v80
	v_fmamk_f32 v80, v107, 0x3fb8aa3b, v106
	v_cvt_pk_bf16_f32 v77, v81, v82
	v_exp_f32_e32 v80, v80
	v_fmamk_f32 v81, v109, 0x3fb8aa3b, v106
	v_exp_f32_e32 v81, v81
	v_fmamk_f32 v82, v102, 0x3fb8aa3b, v106
	v_add_f32_e32 v79, v78, v83
	v_exp_f32_e32 v82, v82
	v_fmamk_f32 v83, v104, 0x3fb8aa3b, v106
	v_exp_f32_e32 v83, v83
	v_fmamk_f32 v84, v103, 0x3fb8aa3b, v106
	v_add_f32_e32 v79, v80, v79
	v_exp_f32_e32 v84, v84
	v_fmamk_f32 v85, v105, 0x3fb8aa3b, v106
	v_add_f32_e32 v79, v81, v79
	v_exp_f32_e32 v85, v85
	v_fmamk_f32 v99, v99, 0x3fb8aa3b, v106
	v_add_f32_e32 v79, v82, v79
	v_exp_f32_e32 v99, v99
	v_add_f32_e32 v79, v83, v79
	v_add_f32_e32 v79, v84, v79
	v_add_f32_e32 v79, v85, v79
	v_add_f32_e32 v102, v99, v79
	v_cvt_pk_bf16_f32 v78, v78, v80
	v_cvt_pk_bf16_f32 v79, v81, v82
	v_fmamk_f32 v82, v100, 0x3fb8aa3b, v106
	v_cvt_pk_bf16_f32 v80, v83, v84
	v_exp_f32_e32 v82, v82
	v_fmamk_f32 v84, v98, 0x3fb8aa3b, v106
	v_cvt_pk_bf16_f32 v81, v85, v99
	v_exp_f32_e32 v84, v84
	v_fmamk_f32 v85, v101, 0x3fb8aa3b, v106
	v_exp_f32_e32 v85, v85
	v_fmamk_f32 v94, v94, 0x3fb8aa3b, v106
	v_exp_f32_e32 v94, v94
	v_fmamk_f32 v96, v96, 0x3fb8aa3b, v106
	v_add_f32_e32 v83, v82, v102
	v_exp_f32_e32 v96, v96
	v_fmamk_f32 v95, v95, 0x3fb8aa3b, v106
	v_add_f32_e32 v83, v84, v83
	v_exp_f32_e32 v95, v95
	v_fmamk_f32 v97, v97, 0x3fb8aa3b, v106
	v_add_f32_e32 v83, v85, v83
	v_exp_f32_e32 v97, v97
	v_fmamk_f32 v91, v91, 0x3fb8aa3b, v106
	v_add_f32_e32 v83, v94, v83
	v_exp_f32_e32 v91, v91
	v_add_f32_e32 v83, v96, v83
	v_add_f32_e32 v83, v95, v83
	v_add_f32_e32 v83, v97, v83
	v_add_f32_e32 v98, v91, v83
	v_cvt_pk_bf16_f32 v82, v82, v84
	v_cvt_pk_bf16_f32 v83, v85, v94
	v_cvt_pk_bf16_f32 v84, v96, v95
	v_cvt_pk_bf16_f32 v85, v97, v91
	v_fmamk_f32 v91, v92, 0x3fb8aa3b, v106
	v_exp_f32_e32 v91, v91
	v_fmamk_f32 v90, v90, 0x3fb8aa3b, v106
	v_exp_f32_e32 v90, v90
	v_fmamk_f32 v93, v93, 0x3fb8aa3b, v106
	v_exp_f32_e32 v93, v93
	v_fmamk_f32 v86, v86, 0x3fb8aa3b, v106
	v_exp_f32_e32 v94, v86
	v_add_f32_e32 v92, v91, v98
	v_add_f32_e32 v92, v90, v92
	v_fmamk_f32 v88, v88, 0x3fb8aa3b, v106
	v_add_f32_e32 v92, v93, v92
	v_exp_f32_e32 v88, v88
	v_fmamk_f32 v87, v87, 0x3fb8aa3b, v106
	v_add_f32_e32 v86, v94, v92
	v_exp_f32_e32 v92, v87
	v_fmamk_f32 v87, v138, 0x3fb8aa3b, v106
	v_exp_f32_e32 v95, v87
	v_fmamk_f32 v87, v89, 0x3fb8aa3b, v106
	v_exp_f32_e32 v89, v87
	v_add_f32_e32 v86, v88, v86
	v_add_f32_e32 v86, v92, v86
	v_add_f32_e32 v86, v95, v86
	v_add_f32_e32 v96, v89, v86
	v_cvt_pk_bf16_f32 v86, v91, v90
	v_fmamk_f32 v90, v137, 0x3fb8aa3b, v106
	v_cvt_pk_bf16_f32 v87, v93, v94
	v_cvt_pk_bf16_f32 v88, v88, v92
	v_exp_f32_e32 v90, v90
	v_fmamk_f32 v92, v136, 0x3fb8aa3b, v106
	v_exp_f32_e32 v92, v92
	v_fmamk_f32 v93, v141, 0x3fb8aa3b, v106
	v_exp_f32_e32 v93, v93
	v_fmamk_f32 v94, v139, 0x3fb8aa3b, v106
	v_cvt_pk_bf16_f32 v89, v95, v89
	v_exp_f32_e32 v95, v94
; __device__ __forceinline__ unsigned cvt_pk_bf16(float lo, float hi) { unsigned r; asm volatile("v_cvt_pk_bf16_f32 %0, %1, %2" : "=v"(r) : "v"(lo), "v"(hi)); return r; }
; __device__ __forceinline__ float fast_exp2(float x) { return __builtin_amdgcn_exp2f(x); }
; template <bool LOCAL>
; __device__ __forceinline__ void attn_unit(const bf16_t* Q, const bf16_t* KT, const bf16_t* VT, bf16_t* O, LAS unsigned char* lds, int b, int h, int r, int w, int tq, int lane) {
;     ...
;     float sum = 0.f; const float mxl = mx * 1.4426950408889634f;
;     bf16x8 pb[NP];
; #pragma unroll
;     for (int p = 0; p < NP; ++p) { float e[8];
; #pragma unroll
;         for (int f = 0; f < 2; ++f)
; #pragma unroll
;             for (int j = 0; j < 4; ++j) { e[4 * f + j] = fast_exp2(fmaf(s[2 * p + f][j], 1.4426950408889634f, -mxl)); sum += e[4 * f + j]; }
;         u32x4 pw; pw.x = cvt_pk_bf16(e[0], e[1]); pw.y = cvt_pk_bf16(e[2], e[3]); pw.z = cvt_pk_bf16(e[4], e[5]); pw.w = cvt_pk_bf16(e[6], e[7]);
;         pb[p] = __builtin_bit_cast(bf16x8, pw); }
	v_fmamk_f32 v94, v195, 0x3fb8aa3b, v106
	v_add_f32_e32 v91, v90, v96
	v_exp_f32_e32 v96, v94
	v_fmamk_f32 v94, v140, 0x3fb8aa3b, v106
	v_add_f32_e32 v91, v92, v91
	v_exp_f32_e32 v97, v94
	v_fmamk_f32 v94, v199, 0x3fb8aa3b, v106
	v_add_f32_e32 v91, v93, v91
	v_exp_f32_e32 v98, v94
	v_fmamk_f32 v94, v197, 0x3fb8aa3b, v106
	v_add_f32_e32 v91, v95, v91
	v_exp_f32_e32 v99, v94
	v_cvt_pk_bf16_f32 v94, v90, v92
	v_fmamk_f32 v90, v198, 0x3fb8aa3b, v106
	v_add_f32_e32 v91, v96, v91
	v_exp_f32_e32 v90, v90
	v_fmamk_f32 v92, v196, 0x3fb8aa3b, v106
	v_add_f32_e32 v91, v97, v91
	v_cvt_pk_bf16_f32 v95, v93, v95
	v_exp_f32_e32 v92, v92
	v_fmamk_f32 v93, v202, 0x3fb8aa3b, v106
	v_add_f32_e32 v91, v98, v91
	v_cvt_pk_bf16_f32 v96, v96, v97
	v_cvt_pk_bf16_f32 v97, v98, v99
	v_exp_f32_e32 v93, v93
	v_fmamk_f32 v98, v200, 0x3fb8aa3b, v106
	v_add_f32_e32 v91, v99, v91
	v_exp_f32_e32 v98, v98
	v_fmamk_f32 v99, v203, 0x3fb8aa3b, v106
	v_add_f32_e32 v91, v90, v91
	v_exp_f32_e32 v99, v99
	v_fmamk_f32 v100, v201, 0x3fb8aa3b, v106
	v_add_f32_e32 v91, v92, v91
	v_exp_f32_e32 v100, v100
	v_fmamk_f32 v101, v205, 0x3fb8aa3b, v106
	v_add_f32_e32 v91, v93, v91
	v_exp_f32_e32 v101, v101
	v_fmamk_f32 v102, v204, 0x3fb8aa3b, v106
	v_add_f32_e32 v91, v98, v91
	v_exp_f32_e32 v105, v102
	v_fmamk_f32 v2, v2, 0x3fb8aa3b, v106
	v_add_f32_e32 v91, v99, v91
	v_exp_f32_e32 v2, v2
	v_fmamk_f32 v3, v3, 0x3fb8aa3b, v106
	v_add_f32_e32 v91, v100, v91
	v_exp_f32_e32 v3, v3
	v_fmamk_f32 v4, v4, 0x3fb8aa3b, v106
	v_add_f32_e32 v91, v101, v91
	v_exp_f32_e32 v4, v4
	v_fmamk_f32 v5, v5, 0x3fb8aa3b, v106
	v_add_f32_e32 v91, v105, v91
	v_exp_f32_e32 v5, v5
	v_fmamk_f32 v10, v10, 0x3fb8aa3b, v106
	v_cvt_pk_bf16_f32 v102, v90, v92
	v_add_f32_e32 v90, v2, v91
	v_exp_f32_e32 v10, v10
	v_fmamk_f32 v11, v11, 0x3fb8aa3b, v106
	v_add_f32_e32 v90, v3, v90
	v_exp_f32_e32 v11, v11
	v_fmamk_f32 v12, v12, 0x3fb8aa3b, v106
	v_add_f32_e32 v90, v4, v90
	v_exp_f32_e32 v12, v12
	v_fmamk_f32 v13, v13, 0x3fb8aa3b, v106
	v_cvt_pk_bf16_f32 v103, v93, v98
	v_cvt_pk_bf16_f32 v104, v99, v100
	v_cvt_pk_bf16_f32 v105, v101, v105
	v_add_f32_e32 v90, v5, v90
	v_exp_f32_e32 v13, v13
	v_cvt_pk_bf16_f32 v98, v2, v3
	v_fmamk_f32 v2, v6, 0x3fb8aa3b, v106
	v_add_f32_e32 v90, v10, v90
	v_cvt_pk_bf16_f32 v99, v4, v5
	v_exp_f32_e32 v2, v2
	v_fmamk_f32 v4, v7, 0x3fb8aa3b, v106
	v_add_f32_e32 v90, v11, v90
	v_exp_f32_e32 v4, v4
	v_fmamk_f32 v5, v8, 0x3fb8aa3b, v106
	v_add_f32_e32 v90, v12, v90
	v_exp_f32_e32 v5, v5
	v_fmamk_f32 v6, v9, 0x3fb8aa3b, v106
	v_add_f32_e32 v90, v13, v90
	v_exp_f32_e32 v6, v6
	v_fmamk_f32 v7, v18, 0x3fb8aa3b, v106
	v_add_f32_e32 v3, v2, v90
	v_exp_f32_e32 v7, v7
	v_fmamk_f32 v8, v19, 0x3fb8aa3b, v106
	v_add_f32_e32 v3, v4, v3
	v_exp_f32_e32 v8, v8
	v_fmamk_f32 v9, v20, 0x3fb8aa3b, v106
	v_cvt_pk_bf16_f32 v100, v10, v11
	v_add_f32_e32 v3, v5, v3
	v_exp_f32_e32 v9, v9
	v_fmamk_f32 v10, v21, 0x3fb8aa3b, v106
	v_cvt_pk_bf16_f32 v101, v12, v13
	v_add_f32_e32 v3, v6, v3
	v_exp_f32_e32 v10, v10
	v_cvt_pk_bf16_f32 v90, v2, v4
	v_fmamk_f32 v2, v14, 0x3fb8aa3b, v106
	v_add_f32_e32 v3, v7, v3
	v_exp_f32_e32 v2, v2
	v_fmamk_f32 v4, v15, 0x3fb8aa3b, v106
	v_add_f32_e32 v3, v8, v3
	v_cvt_pk_bf16_f32 v91, v5, v6
	v_exp_f32_e32 v4, v4
	v_fmamk_f32 v5, v16, 0x3fb8aa3b, v106
	v_add_f32_e32 v3, v9, v3
	v_exp_f32_e32 v5, v5
	v_fmamk_f32 v6, v17, 0x3fb8aa3b, v106
	v_add_f32_e32 v3, v10, v3
	v_cvt_pk_bf16_f32 v92, v7, v8
	v_exp_f32_e32 v6, v6
	v_fmamk_f32 v7, v26, 0x3fb8aa3b, v106
	v_add_f32_e32 v3, v2, v3
	v_exp_f32_e32 v7, v7
	v_fmamk_f32 v8, v27, 0x3fb8aa3b, v106
	v_cvt_pk_bf16_f32 v93, v9, v10
	v_add_f32_e32 v3, v4, v3
	v_exp_f32_e32 v8, v8
	v_fmamk_f32 v9, v28, 0x3fb8aa3b, v106
	v_add_f32_e32 v3, v5, v3
	v_exp_f32_e32 v9, v9
	v_fmamk_f32 v10, v29, 0x3fb8aa3b, v106
	v_add_f32_e32 v3, v6, v3
	v_exp_f32_e32 v10, v10
	v_cvt_pk_bf16_f32 v26, v2, v4
	v_fmamk_f32 v2, v22, 0x3fb8aa3b, v106
	v_add_f32_e32 v3, v7, v3
	v_exp_f32_e32 v2, v2
	v_fmamk_f32 v4, v23, 0x3fb8aa3b, v106
	v_add_f32_e32 v3, v8, v3
	v_cvt_pk_bf16_f32 v27, v5, v6
	v_exp_f32_e32 v4, v4
	v_fmamk_f32 v5, v24, 0x3fb8aa3b, v106
	v_add_f32_e32 v3, v9, v3
	v_exp_f32_e32 v5, v5
	v_fmamk_f32 v6, v25, 0x3fb8aa3b, v106
	v_add_f32_e32 v3, v10, v3
	v_cvt_pk_bf16_f32 v28, v7, v8
	v_exp_f32_e32 v6, v6
	v_fmamk_f32 v7, v34, 0x3fb8aa3b, v106
	v_add_f32_e32 v3, v2, v3
	v_exp_f32_e32 v7, v7
	v_fmamk_f32 v8, v35, 0x3fb8aa3b, v106
	v_cvt_pk_bf16_f32 v29, v9, v10
	v_add_f32_e32 v3, v4, v3
	v_exp_f32_e32 v8, v8
	v_fmamk_f32 v9, v36, 0x3fb8aa3b, v106
	v_add_f32_e32 v3, v5, v3
	v_exp_f32_e32 v9, v9
	v_fmamk_f32 v10, v37, 0x3fb8aa3b, v106
	v_add_f32_e32 v3, v6, v3
	v_exp_f32_e32 v13, v10
	v_cvt_pk_bf16_f32 v10, v2, v4
	v_fmamk_f32 v2, v30, 0x3fb8aa3b, v106
	v_add_f32_e32 v3, v7, v3
	v_exp_f32_e32 v2, v2
	v_fmamk_f32 v4, v31, 0x3fb8aa3b, v106
	v_add_f32_e32 v3, v8, v3
	v_cvt_pk_bf16_f32 v11, v5, v6
	v_exp_f32_e32 v4, v4
	v_fmamk_f32 v5, v32, 0x3fb8aa3b, v106
	v_add_f32_e32 v3, v9, v3
	v_exp_f32_e32 v5, v5
	v_fmamk_f32 v6, v33, 0x3fb8aa3b, v106
	v_add_f32_e32 v3, v13, v3
	v_cvt_pk_bf16_f32 v12, v7, v8
	v_exp_f32_e32 v6, v6
	v_fmamk_f32 v7, v42, 0x3fb8aa3b, v106
	v_add_f32_e32 v3, v2, v3
	v_exp_f32_e32 v7, v7
	v_fmamk_f32 v8, v43, 0x3fb8aa3b, v106
	v_cvt_pk_bf16_f32 v13, v9, v13
	v_add_f32_e32 v3, v4, v3
	v_exp_f32_e32 v8, v8
	v_fmamk_f32 v9, v44, 0x3fb8aa3b, v106
	v_add_f32_e32 v3, v5, v3
	v_exp_f32_e32 v9, v9
	v_fmamk_f32 v14, v45, 0x3fb8aa3b, v106
	v_add_f32_e32 v3, v6, v3
	v_exp_f32_e32 v14, v14
	v_add_f32_e32 v3, v7, v3
	v_add_f32_e32 v3, v8, v3
	v_add_f32_e32 v3, v9, v3
	v_add_f32_e32 v15, v14, v3
	v_cvt_pk_bf16_f32 v2, v2, v4
	v_cvt_pk_bf16_f32 v3, v5, v6
	v_fmamk_f32 v6, v38, 0x3fb8aa3b, v106
; __device__ __forceinline__ unsigned cvt_pk_bf16(float lo, float hi) { unsigned r; asm volatile("v_cvt_pk_bf16_f32 %0, %1, %2" : "=v"(r) : "v"(lo), "v"(hi)); return r; }
; __device__ __forceinline__ float fast_exp2(float x) { return __builtin_amdgcn_exp2f(x); }
; #define ATT_VLOAD(buf, p) do { const bf16_t* vp_ = vloc + (size_t)((p) * 8 * NH) * 1024; \
;         _Pragma("unroll") for (int df = 0; df < 8; ++df) va[buf][df] = *(const bf16x8*)(vp_ + df * 128); } while (0)
; template <bool LOCAL>
; __device__ __forceinline__ void attn_unit(const bf16_t* Q, const bf16_t* KT, const bf16_t* VT, bf16_t* O, LAS unsigned char* lds, int b, int h, int r, int w, int tq, int lane) {
;     ...
;             for (int j = 0; j < 4; ++j) { e[4 * f + j] = fast_exp2(fmaf(s[2 * p + f][j], 1.4426950408889634f, -mxl)); sum += e[4 * f + j]; }
;         u32x4 pw; pw.x = cvt_pk_bf16(e[0], e[1]); pw.y = cvt_pk_bf16(e[2], e[3]); pw.z = cvt_pk_bf16(e[4], e[5]); pw.w = cvt_pk_bf16(e[6], e[7]);
;         pb[p] = __builtin_bit_cast(bf16x8, pw); }
;     sum += __shfl_xor(sum, 16); sum += __shfl_xor(sum, 32);
;     f32x4 o[8];
; #pragma unroll
;     for (int df = 0; df < 8; ++df) o[df] = (f32x4){0.f, 0.f, 0.f, 0.f};
;     if (LOCAL) {
;         const bf16_t* vloc = VT + ((size_t)(((rgl >> 3) + g) * NH + h)) * 1024 + q * 8;
;         bf16x8 va[2][8];
;     ...
;         ATT_VLOAD(0, 0);
; #pragma unroll
;         for (int p = 0; p < 8; ++p) {
;             __builtin_amdgcn_s_barrier();
;             if (p + 1 < 8) ATT_VLOAD((p + 1) & 1, p + 1);
;             __builtin_amdgcn_sched_barrier(0);
; #pragma unroll
;             for (int df = 0; df < 8; ++df) o[df] = __builtin_amdgcn_mfma_f32_16x16x32_bf16(va[p & 1][df], pb[p], o[df], 0, 0, 0);
;             __builtin_amdgcn_sched_barrier(0);
;         }
;     ...
;     }
	v_exp_f32_e32 v6, v6
	v_cvt_pk_bf16_f32 v4, v7, v8
	v_fmamk_f32 v8, v39, 0x3fb8aa3b, v106
	v_cvt_pk_bf16_f32 v5, v9, v14
	v_exp_f32_e32 v8, v8
	v_fmamk_f32 v9, v40, 0x3fb8aa3b, v106
	v_exp_f32_e32 v9, v9
	v_fmamk_f32 v14, v41, 0x3fb8aa3b, v106
	v_add_f32_e32 v7, v6, v15
	v_exp_f32_e32 v14, v14
	v_fmamk_f32 v15, v50, 0x3fb8aa3b, v106
	v_exp_f32_e32 v15, v15
	v_fmamk_f32 v16, v51, 0x3fb8aa3b, v106
	v_add_f32_e32 v7, v8, v7
	v_exp_f32_e32 v16, v16
	v_fmamk_f32 v17, v52, 0x3fb8aa3b, v106
	v_add_f32_e32 v7, v9, v7
	v_exp_f32_e32 v17, v17
	v_fmamk_f32 v18, v53, 0x3fb8aa3b, v106
	v_add_f32_e32 v7, v14, v7
	v_exp_f32_e32 v18, v18
	v_add_f32_e32 v7, v15, v7
	v_add_f32_e32 v7, v16, v7
	v_add_f32_e32 v7, v17, v7
	v_add_f32_e32 v19, v18, v7
	v_cvt_pk_bf16_f32 v6, v6, v8
	v_cvt_pk_bf16_f32 v7, v9, v14
	v_fmamk_f32 v14, v46, 0x3fb8aa3b, v106
	v_exp_f32_e32 v14, v14
	v_cvt_pk_bf16_f32 v8, v15, v16
	v_fmamk_f32 v16, v47, 0x3fb8aa3b, v106
	v_cvt_pk_bf16_f32 v9, v17, v18
	v_exp_f32_e32 v16, v16
	v_fmamk_f32 v17, v48, 0x3fb8aa3b, v106
	v_exp_f32_e32 v17, v17
	v_fmamk_f32 v18, v49, 0x3fb8aa3b, v106
	v_add_f32_e32 v15, v14, v19
	v_exp_f32_e32 v18, v18
	v_fmamk_f32 v19, v58, 0x3fb8aa3b, v106
	v_exp_f32_e32 v19, v19
	v_fmamk_f32 v20, v59, 0x3fb8aa3b, v106
	v_add_f32_e32 v15, v16, v15
	v_exp_f32_e32 v20, v20
	v_fmamk_f32 v21, v60, 0x3fb8aa3b, v106
	v_add_f32_e32 v15, v17, v15
	v_exp_f32_e32 v21, v21
	v_fmamk_f32 v22, v61, 0x3fb8aa3b, v106
	v_add_f32_e32 v15, v18, v15
	v_exp_f32_e32 v22, v22
	v_add_f32_e32 v15, v19, v15
	v_add_f32_e32 v15, v20, v15
	v_add_f32_e32 v15, v21, v15
	v_add_f32_e32 v23, v22, v15
	v_cvt_pk_bf16_f32 v14, v14, v16
	v_cvt_pk_bf16_f32 v15, v17, v18
	v_fmamk_f32 v18, v54, 0x3fb8aa3b, v106
	v_exp_f32_e32 v18, v18
	v_cvt_pk_bf16_f32 v16, v19, v20
	v_fmamk_f32 v20, v55, 0x3fb8aa3b, v106
	v_cvt_pk_bf16_f32 v17, v21, v22
	v_exp_f32_e32 v20, v20
	v_fmamk_f32 v21, v56, 0x3fb8aa3b, v106
	v_exp_f32_e32 v21, v21
	v_fmamk_f32 v22, v57, 0x3fb8aa3b, v106
	v_add_f32_e32 v19, v18, v23
	v_exp_f32_e32 v22, v22
	v_fmamk_f32 v23, v62, 0x3fb8aa3b, v106
	v_exp_f32_e32 v23, v23
	v_fmamk_f32 v24, v63, 0x3fb8aa3b, v106
	v_add_f32_e32 v19, v20, v19
	v_exp_f32_e32 v24, v24
	v_fmamk_f32 v25, v64, 0x3fb8aa3b, v106
	v_add_f32_e32 v19, v21, v19
	v_exp_f32_e32 v25, v25
	v_fmac_f32_e32 v106, 0x3fb8aa3b, v65
	v_add_f32_e32 v19, v22, v19
	v_exp_f32_e32 v30, v106
	v_add_f32_e32 v19, v23, v19
	v_add_f32_e32 v19, v24, v19
	v_add_f32_e32 v19, v25, v19
	v_add_f32_e32 v31, v30, v19
	v_cvt_pk_bf16_f32 v18, v18, v20
	v_cvt_pk_bf16_f32 v19, v21, v22
	ds_bpermute_b32 v22, v181, v31
	v_cvt_pk_bf16_f32 v20, v23, v24
	v_cvt_pk_bf16_f32 v21, v25, v30
	s_waitcnt lgkmcnt(0)
	v_add_f32_e32 v134, v31, v22
	v_add_u32_e32 v22, v194, v165
	v_lshl_or_b32 v22, v22, 4, s72
	v_ashrrev_i32_e32 v23, 31, v22
	v_lshlrev_b64 v[22:23], 11, v[22:23]
	v_lshl_add_u64 v[132:133], v[148:149], 0, v[22:23]
	ds_bpermute_b32 v135, v182, v134
	v_lshlrev_b32_e32 v218, 4, v164
	v_add_u32_e32 v218, s28, v218
	ds_read_b64 v[220:221], v241 offset:192
	s_waitcnt lgkmcnt(0)
	v_add_co_u32_e32 v220, vcc, 0x24300000, v220
	s_nop 1
	v_addc_co_u32_e32 v221, vcc, 0, v221, vcc
	v_add_co_u32_e32 v220, vcc, v220, v218
	s_nop 1
	v_addc_co_u32_e32 v221, vcc, 0, v221, vcc
	s_and_b32 s55, s57, 3
	s_lshl_b32 s55, s55, 1
	s_add_i32 s55, s55, -1
	s_max_i32 s55, s55, 0
	s_min_i32 s55, s55, 4
	v_add_u32_e32 v219, s55, v165
	v_lshlrev_b32_e32 v224, 4, v166
	v_lshl_add_u32 v219, v219, 10, v224
	v_add_u32_e32 v219, 0x21000, v219
	s_barrier
	s_add_i32 m0, s59, 0
	s_nop 0
	global_load_lds_dwordx4 v[220:221], off
	s_add_i32 m0, s59, 7168
	s_nop 0
	global_load_lds_dwordx4 v[220:221], off offset:1024
	s_cmp_eq_u32 s53, 0
	s_cbranch_scc0 .Lring_v_B
	s_waitcnt vmcnt(1)
	s_barrier
	s_add_i32 m0, s59, 16384
	v_add_co_u32_e32 v222, vcc, s6, v220
	s_nop 1
	v_addc_co_u32_e32 v223, vcc, 0, v221, vcc
	global_load_lds_dwordx4 v[222:223], off
	ds_read_b128 v[106:109], v219 offset:0
	ds_read_b128 v[110:113], v219 offset:256
	ds_read_b128 v[114:117], v219 offset:512
	ds_read_b128 v[118:121], v219 offset:768
	s_waitcnt lgkmcnt(3)
	v_mfma_f32_16x16x32_bf16 v[22:25], v[106:109], v[66:69], 0
	s_waitcnt lgkmcnt(2)
	v_mfma_f32_16x16x32_bf16 v[30:33], v[110:113], v[66:69], 0
	s_waitcnt lgkmcnt(1)
	v_mfma_f32_16x16x32_bf16 v[34:37], v[114:117], v[66:69], 0
	s_waitcnt lgkmcnt(0)
	v_mfma_f32_16x16x32_bf16 v[38:41], v[118:121], v[66:69], 0
	s_waitcnt vmcnt(1)
	s_barrier
	s_add_i32 m0, s59, -1024
	v_add_co_u32_e32 v222, vcc, s6, v220
	s_nop 1
	v_addc_co_u32_e32 v223, vcc, 0, v221, vcc
	global_load_lds_dwordx4 v[222:223], off offset:1024
	ds_read_b128 v[122:125], v219 offset:8192
	ds_read_b128 v[126:129], v219 offset:8448
	ds_read_b128 v[58:61], v219 offset:8704
	ds_read_b128 v[62:65], v219 offset:8960
	s_waitcnt lgkmcnt(3)
	v_mfma_f32_16x16x32_bf16 v[42:45], v[122:125], v[66:69], 0
	s_waitcnt lgkmcnt(2)
	v_mfma_f32_16x16x32_bf16 v[46:49], v[126:129], v[66:69], 0
	s_waitcnt lgkmcnt(1)
	v_mfma_f32_16x16x32_bf16 v[50:53], v[58:61], v[66:69], 0
	s_waitcnt lgkmcnt(0)
	v_mfma_f32_16x16x32_bf16 v[54:57], v[62:65], v[66:69], 0
	s_waitcnt vmcnt(1)
	s_barrier
	s_add_i32 m0, s59, 8192
	v_add_co_u32_e32 v222, vcc, s7, v220
	s_nop 1
	v_addc_co_u32_e32 v223, vcc, 0, v221, vcc
	global_load_lds_dwordx4 v[222:223], off
	ds_read_b128 v[106:109], v219 offset:16384
	ds_read_b128 v[110:113], v219 offset:16640
	ds_read_b128 v[114:117], v219 offset:16896
	ds_read_b128 v[118:121], v219 offset:17152
	s_waitcnt lgkmcnt(3)
	v_mfma_f32_16x16x32_bf16 v[22:25], v[106:109], v[70:73], v[22:25]
	s_waitcnt lgkmcnt(2)
	v_mfma_f32_16x16x32_bf16 v[30:33], v[110:113], v[70:73], v[30:33]
	s_waitcnt lgkmcnt(1)
	v_mfma_f32_16x16x32_bf16 v[34:37], v[114:117], v[70:73], v[34:37]
	s_waitcnt lgkmcnt(0)
	v_mfma_f32_16x16x32_bf16 v[38:41], v[118:121], v[70:73], v[38:41]
	s_waitcnt vmcnt(1)
	s_barrier
; #define ATT_VLOAD(buf, p) do { const bf16_t* vp_ = vloc + (size_t)((p) * 8 * NH) * 1024; \
;         _Pragma("unroll") for (int df = 0; df < 8; ++df) va[buf][df] = *(const bf16x8*)(vp_ + df * 128); } while (0)
; template <bool LOCAL>
; __device__ __forceinline__ void attn_unit(const bf16_t* Q, const bf16_t* KT, const bf16_t* VT, bf16_t* O, LAS unsigned char* lds, int b, int h, int r, int w, int tq, int lane) {
;     ...
;     if (LOCAL) {
;         const bf16_t* vloc = VT + ((size_t)(((rgl >> 3) + g) * NH + h)) * 1024 + q * 8;
;         bf16x8 va[2][8];
;     ...
;         ATT_VLOAD(0, 0);
; #pragma unroll
;         for (int p = 0; p < 8; ++p) {
;             __builtin_amdgcn_s_barrier();
;             if (p + 1 < 8) ATT_VLOAD((p + 1) & 1, p + 1);
;             __builtin_amdgcn_sched_barrier(0);
; #pragma unroll
;             for (int df = 0; df < 8; ++df) o[df] = __builtin_amdgcn_mfma_f32_16x16x32_bf16(va[p & 1][df], pb[p], o[df], 0, 0, 0);
;             __builtin_amdgcn_sched_barrier(0);
;         }
	s_add_i32 m0, s59, 15360
	v_add_co_u32_e32 v222, vcc, s7, v220
	s_nop 1
	v_addc_co_u32_e32 v223, vcc, 0, v221, vcc
	global_load_lds_dwordx4 v[222:223], off offset:1024
	ds_read_b128 v[122:125], v219 offset:0
	ds_read_b128 v[126:129], v219 offset:256
	ds_read_b128 v[58:61], v219 offset:512
	ds_read_b128 v[62:65], v219 offset:768
	s_waitcnt lgkmcnt(3)
	v_mfma_f32_16x16x32_bf16 v[42:45], v[122:125], v[70:73], v[42:45]
	s_waitcnt lgkmcnt(2)
	v_mfma_f32_16x16x32_bf16 v[46:49], v[126:129], v[70:73], v[46:49]
	s_waitcnt lgkmcnt(1)
	v_mfma_f32_16x16x32_bf16 v[50:53], v[58:61], v[70:73], v[50:53]
	s_waitcnt lgkmcnt(0)
	v_mfma_f32_16x16x32_bf16 v[54:57], v[62:65], v[70:73], v[54:57]
	s_waitcnt vmcnt(1)
	s_barrier
	s_add_i32 m0, s59, 0
	v_add_co_u32_e32 v222, vcc, s2, v220
	s_nop 1
	v_addc_co_u32_e32 v223, vcc, 0, v221, vcc
	global_load_lds_dwordx4 v[222:223], off
	ds_read_b128 v[106:109], v219 offset:8192
	ds_read_b128 v[110:113], v219 offset:8448
	ds_read_b128 v[114:117], v219 offset:8704
	ds_read_b128 v[118:121], v219 offset:8960
	s_waitcnt lgkmcnt(3)
	v_mfma_f32_16x16x32_bf16 v[22:25], v[106:109], v[74:77], v[22:25]
	s_waitcnt lgkmcnt(2)
	v_mfma_f32_16x16x32_bf16 v[30:33], v[110:113], v[74:77], v[30:33]
	s_waitcnt lgkmcnt(1)
	v_mfma_f32_16x16x32_bf16 v[34:37], v[114:117], v[74:77], v[34:37]
	s_waitcnt lgkmcnt(0)
	v_mfma_f32_16x16x32_bf16 v[38:41], v[118:121], v[74:77], v[38:41]
	s_waitcnt vmcnt(1)
	s_barrier
	s_add_i32 m0, s59, 7168
	v_add_co_u32_e32 v222, vcc, s2, v220
	s_nop 1
	v_addc_co_u32_e32 v223, vcc, 0, v221, vcc
	global_load_lds_dwordx4 v[222:223], off offset:1024
	ds_read_b128 v[122:125], v219 offset:16384
	ds_read_b128 v[126:129], v219 offset:16640
	ds_read_b128 v[58:61], v219 offset:16896
	ds_read_b128 v[62:65], v219 offset:17152
	s_waitcnt lgkmcnt(3)
	v_mfma_f32_16x16x32_bf16 v[42:45], v[122:125], v[74:77], v[42:45]
	s_waitcnt lgkmcnt(2)
	v_mfma_f32_16x16x32_bf16 v[46:49], v[126:129], v[74:77], v[46:49]
	s_waitcnt lgkmcnt(1)
	v_mfma_f32_16x16x32_bf16 v[50:53], v[58:61], v[74:77], v[50:53]
	s_waitcnt lgkmcnt(0)
	v_mfma_f32_16x16x32_bf16 v[54:57], v[62:65], v[74:77], v[54:57]
	s_waitcnt vmcnt(1)
	s_barrier
	s_add_i32 m0, s59, 16384
	v_add_co_u32_e32 v222, vcc, s60, v220
	s_nop 1
	v_addc_co_u32_e32 v223, vcc, 0, v221, vcc
	global_load_lds_dwordx4 v[222:223], off
	ds_read_b128 v[106:109], v219 offset:0
	ds_read_b128 v[110:113], v219 offset:256
	ds_read_b128 v[114:117], v219 offset:512
	ds_read_b128 v[118:121], v219 offset:768
	s_waitcnt lgkmcnt(3)
	v_mfma_f32_16x16x32_bf16 v[22:25], v[106:109], v[78:81], v[22:25]
	s_waitcnt lgkmcnt(2)
	v_mfma_f32_16x16x32_bf16 v[30:33], v[110:113], v[78:81], v[30:33]
	s_waitcnt lgkmcnt(1)
	v_mfma_f32_16x16x32_bf16 v[34:37], v[114:117], v[78:81], v[34:37]
	s_waitcnt lgkmcnt(0)
	v_mfma_f32_16x16x32_bf16 v[38:41], v[118:121], v[78:81], v[38:41]
	s_waitcnt vmcnt(1)
	s_barrier
	s_add_i32 m0, s59, -1024
	v_add_co_u32_e32 v222, vcc, s60, v220
	s_nop 1
	v_addc_co_u32_e32 v223, vcc, 0, v221, vcc
	global_load_lds_dwordx4 v[222:223], off offset:1024
	ds_read_b128 v[122:125], v219 offset:8192
	ds_read_b128 v[126:129], v219 offset:8448
	ds_read_b128 v[58:61], v219 offset:8704
	ds_read_b128 v[62:65], v219 offset:8960
	s_waitcnt lgkmcnt(3)
	v_mfma_f32_16x16x32_bf16 v[42:45], v[122:125], v[78:81], v[42:45]
	s_waitcnt lgkmcnt(2)
	v_mfma_f32_16x16x32_bf16 v[46:49], v[126:129], v[78:81], v[46:49]
	s_waitcnt lgkmcnt(1)
	v_mfma_f32_16x16x32_bf16 v[50:53], v[58:61], v[78:81], v[50:53]
	s_waitcnt lgkmcnt(0)
	v_mfma_f32_16x16x32_bf16 v[54:57], v[62:65], v[78:81], v[54:57]
	s_waitcnt vmcnt(1)
	s_barrier
	s_add_i32 m0, s59, 8192
	v_add_co_u32_e32 v222, vcc, s61, v220
	s_nop 1
	v_addc_co_u32_e32 v223, vcc, 0, v221, vcc
	global_load_lds_dwordx4 v[222:223], off
	ds_read_b128 v[106:109], v219 offset:16384
	ds_read_b128 v[110:113], v219 offset:16640
	ds_read_b128 v[114:117], v219 offset:16896
	ds_read_b128 v[118:121], v219 offset:17152
	s_waitcnt lgkmcnt(3)
	v_mfma_f32_16x16x32_bf16 v[22:25], v[106:109], v[82:85], v[22:25]
	s_waitcnt lgkmcnt(2)
	v_mfma_f32_16x16x32_bf16 v[30:33], v[110:113], v[82:85], v[30:33]
	s_waitcnt lgkmcnt(1)
	v_mfma_f32_16x16x32_bf16 v[34:37], v[114:117], v[82:85], v[34:37]
	s_waitcnt lgkmcnt(0)
	v_mfma_f32_16x16x32_bf16 v[38:41], v[118:121], v[82:85], v[38:41]
	s_waitcnt vmcnt(1)
	s_barrier
; #define ATT_VLOAD(buf, p) do { const bf16_t* vp_ = vloc + (size_t)((p) * 8 * NH) * 1024; \
;         _Pragma("unroll") for (int df = 0; df < 8; ++df) va[buf][df] = *(const bf16x8*)(vp_ + df * 128); } while (0)
; template <bool LOCAL>
; __device__ __forceinline__ void attn_unit(const bf16_t* Q, const bf16_t* KT, const bf16_t* VT, bf16_t* O, LAS unsigned char* lds, int b, int h, int r, int w, int tq, int lane) {
;     ...
;     if (LOCAL) {
;         const bf16_t* vloc = VT + ((size_t)(((rgl >> 3) + g) * NH + h)) * 1024 + q * 8;
;         bf16x8 va[2][8];
;     ...
;         ATT_VLOAD(0, 0);
; #pragma unroll
;         for (int p = 0; p < 8; ++p) {
;             __builtin_amdgcn_s_barrier();
;             if (p + 1 < 8) ATT_VLOAD((p + 1) & 1, p + 1);
;             __builtin_amdgcn_sched_barrier(0);
; #pragma unroll
;             for (int df = 0; df < 8; ++df) o[df] = __builtin_amdgcn_mfma_f32_16x16x32_bf16(va[p & 1][df], pb[p], o[df], 0, 0, 0);
;             __builtin_amdgcn_sched_barrier(0);
;         }
	s_add_i32 m0, s59, 15360
	v_add_co_u32_e32 v222, vcc, s61, v220
	s_nop 1
	v_addc_co_u32_e32 v223, vcc, 0, v221, vcc
	global_load_lds_dwordx4 v[222:223], off offset:1024
	ds_read_b128 v[122:125], v219 offset:0
	ds_read_b128 v[126:129], v219 offset:256
	ds_read_b128 v[58:61], v219 offset:512
	ds_read_b128 v[62:65], v219 offset:768
	s_waitcnt lgkmcnt(3)
	v_mfma_f32_16x16x32_bf16 v[42:45], v[122:125], v[82:85], v[42:45]
	s_waitcnt lgkmcnt(2)
	v_mfma_f32_16x16x32_bf16 v[46:49], v[126:129], v[82:85], v[46:49]
	s_waitcnt lgkmcnt(1)
	v_mfma_f32_16x16x32_bf16 v[50:53], v[58:61], v[82:85], v[50:53]
	s_waitcnt lgkmcnt(0)
	v_mfma_f32_16x16x32_bf16 v[54:57], v[62:65], v[82:85], v[54:57]
	s_waitcnt vmcnt(1)
	s_barrier
	s_add_i32 m0, s59, 0
	v_add_co_u32_e32 v222, vcc, s17, v220
	s_nop 1
	v_addc_co_u32_e32 v223, vcc, 0, v221, vcc
	global_load_lds_dwordx4 v[222:223], off
	ds_read_b128 v[106:109], v219 offset:8192
	ds_read_b128 v[110:113], v219 offset:8448
	ds_read_b128 v[114:117], v219 offset:8704
	ds_read_b128 v[118:121], v219 offset:8960
	s_waitcnt lgkmcnt(3)
	v_mfma_f32_16x16x32_bf16 v[22:25], v[106:109], v[86:89], v[22:25]
	s_waitcnt lgkmcnt(2)
	v_mfma_f32_16x16x32_bf16 v[30:33], v[110:113], v[86:89], v[30:33]
	s_waitcnt lgkmcnt(1)
	v_mfma_f32_16x16x32_bf16 v[34:37], v[114:117], v[86:89], v[34:37]
	s_waitcnt lgkmcnt(0)
	v_mfma_f32_16x16x32_bf16 v[38:41], v[118:121], v[86:89], v[38:41]
	s_waitcnt vmcnt(1)
	s_barrier
	s_add_i32 m0, s59, 7168
	v_add_co_u32_e32 v222, vcc, s17, v220
	s_nop 1
	v_addc_co_u32_e32 v223, vcc, 0, v221, vcc
	global_load_lds_dwordx4 v[222:223], off offset:1024
	ds_read_b128 v[122:125], v219 offset:16384
	ds_read_b128 v[126:129], v219 offset:16640
	ds_read_b128 v[58:61], v219 offset:16896
	ds_read_b128 v[62:65], v219 offset:17152
	s_waitcnt lgkmcnt(3)
	v_mfma_f32_16x16x32_bf16 v[42:45], v[122:125], v[86:89], v[42:45]
	s_waitcnt lgkmcnt(2)
	v_mfma_f32_16x16x32_bf16 v[46:49], v[126:129], v[86:89], v[46:49]
	s_waitcnt lgkmcnt(1)
	v_mfma_f32_16x16x32_bf16 v[50:53], v[58:61], v[86:89], v[50:53]
	s_waitcnt lgkmcnt(0)
	v_mfma_f32_16x16x32_bf16 v[54:57], v[62:65], v[86:89], v[54:57]
	s_waitcnt vmcnt(1)
	s_barrier
	s_add_i32 m0, s59, 16384
	v_add_co_u32_e32 v222, vcc, s62, v220
	s_nop 1
	v_addc_co_u32_e32 v223, vcc, 0, v221, vcc
	global_load_lds_dwordx4 v[222:223], off
	ds_read_b128 v[106:109], v219 offset:0
	ds_read_b128 v[110:113], v219 offset:256
	ds_read_b128 v[114:117], v219 offset:512
	ds_read_b128 v[118:121], v219 offset:768
	s_waitcnt lgkmcnt(3)
	v_mfma_f32_16x16x32_bf16 v[22:25], v[106:109], v[94:97], v[22:25]
	s_waitcnt lgkmcnt(2)
	v_mfma_f32_16x16x32_bf16 v[30:33], v[110:113], v[94:97], v[30:33]
	s_waitcnt lgkmcnt(1)
	v_mfma_f32_16x16x32_bf16 v[34:37], v[114:117], v[94:97], v[34:37]
	s_waitcnt lgkmcnt(0)
	v_mfma_f32_16x16x32_bf16 v[38:41], v[118:121], v[94:97], v[38:41]
	s_waitcnt vmcnt(1)
	s_barrier
	s_add_i32 m0, s59, -1024
	v_add_co_u32_e32 v222, vcc, s62, v220
	s_nop 1
	v_addc_co_u32_e32 v223, vcc, 0, v221, vcc
	global_load_lds_dwordx4 v[222:223], off offset:1024
	ds_read_b128 v[122:125], v219 offset:8192
	ds_read_b128 v[126:129], v219 offset:8448
	ds_read_b128 v[58:61], v219 offset:8704
	ds_read_b128 v[62:65], v219 offset:8960
	s_waitcnt lgkmcnt(3)
	v_mfma_f32_16x16x32_bf16 v[42:45], v[122:125], v[94:97], v[42:45]
	s_waitcnt lgkmcnt(2)
	v_mfma_f32_16x16x32_bf16 v[46:49], v[126:129], v[94:97], v[46:49]
	s_waitcnt lgkmcnt(1)
	v_mfma_f32_16x16x32_bf16 v[50:53], v[58:61], v[94:97], v[50:53]
	s_waitcnt lgkmcnt(0)
	v_mfma_f32_16x16x32_bf16 v[54:57], v[62:65], v[94:97], v[54:57]
	s_waitcnt vmcnt(1)
	s_barrier
	s_cmp_eq_u32 s73, 0
	s_cbranch_scc1 .Lring_v_A_nd14
	s_add_i32 m0, s59, 8192
	v_add_co_u32_e32 v222, vcc, s75, v220
	s_nop 1
	v_addc_co_u32_e32 v223, vcc, 0, v221, vcc
	global_load_lds_dwordx4 v[222:223], off
.Lring_v_A_nd14:
	ds_read_b128 v[106:109], v219 offset:16384
	ds_read_b128 v[110:113], v219 offset:16640
	ds_read_b128 v[114:117], v219 offset:16896
	ds_read_b128 v[118:121], v219 offset:17152
	s_waitcnt lgkmcnt(3)
	v_mfma_f32_16x16x32_bf16 v[22:25], v[106:109], v[102:105], v[22:25]
	s_waitcnt lgkmcnt(2)
	v_mfma_f32_16x16x32_bf16 v[30:33], v[110:113], v[102:105], v[30:33]
	s_waitcnt lgkmcnt(1)
	v_mfma_f32_16x16x32_bf16 v[34:37], v[114:117], v[102:105], v[34:37]
	s_waitcnt lgkmcnt(0)
	v_mfma_f32_16x16x32_bf16 v[38:41], v[118:121], v[102:105], v[38:41]
	s_cmp_eq_u32 s73, 0
	s_cbranch_scc1 .Lring_v_A_w15
	s_waitcnt vmcnt(1)
	s_branch .Lring_v_A_b15

; #define ATT_VLOAD(buf, p) do { const bf16_t* vp_ = vloc + (size_t)((p) * 8 * NH) * 1024; \
;         _Pragma("unroll") for (int df = 0; df < 8; ++df) va[buf][df] = *(const bf16x8*)(vp_ + df * 128); } while (0)
; template <bool LOCAL>
; __device__ __forceinline__ void attn_unit(const bf16_t* Q, const bf16_t* KT, const bf16_t* VT, bf16_t* O, LAS unsigned char* lds, int b, int h, int r, int w, int tq, int lane) {
;     ...
;     if (LOCAL) {
;         const bf16_t* vloc = VT + ((size_t)(((rgl >> 3) + g) * NH + h)) * 1024 + q * 8;
;         bf16x8 va[2][8];
;     ...
;         ATT_VLOAD(0, 0);
; #pragma unroll
;         for (int p = 0; p < 8; ++p) {
;             __builtin_amdgcn_s_barrier();
;             if (p + 1 < 8) ATT_VLOAD((p + 1) & 1, p + 1);
;             __builtin_amdgcn_sched_barrier(0);
; #pragma unroll
;             for (int df = 0; df < 8; ++df) o[df] = __builtin_amdgcn_mfma_f32_16x16x32_bf16(va[p & 1][df], pb[p], o[df], 0, 0, 0);
;             __builtin_amdgcn_sched_barrier(0);
;         }
.Lring_v_A_b15:
	s_barrier
	s_cmp_eq_u32 s73, 0
	s_cbranch_scc1 .Lring_v_A_nd15
	s_add_i32 m0, s59, 15360
	v_add_co_u32_e32 v222, vcc, s75, v220
	s_nop 1
	v_addc_co_u32_e32 v223, vcc, 0, v221, vcc
	global_load_lds_dwordx4 v[222:223], off offset:1024
.Lring_v_A_nd15:
	ds_read_b128 v[122:125], v219 offset:0
	ds_read_b128 v[126:129], v219 offset:256
	ds_read_b128 v[58:61], v219 offset:512
	ds_read_b128 v[62:65], v219 offset:768
	s_waitcnt lgkmcnt(3)
	v_mfma_f32_16x16x32_bf16 v[42:45], v[122:125], v[102:105], v[42:45]
	s_waitcnt lgkmcnt(2)
	v_mfma_f32_16x16x32_bf16 v[46:49], v[126:129], v[102:105], v[46:49]
	s_waitcnt lgkmcnt(1)
	v_mfma_f32_16x16x32_bf16 v[50:53], v[58:61], v[102:105], v[50:53]
	s_waitcnt lgkmcnt(0)
	v_mfma_f32_16x16x32_bf16 v[54:57], v[62:65], v[102:105], v[54:57]
	s_cmp_eq_u32 s73, 0
	s_cbranch_scc1 .Lring_v_A_end
	s_waitcnt vmcnt(1)
	s_barrier
	s_waitcnt vmcnt(0)
	s_barrier

; #define ATT_VLOAD(buf, p) do { const bf16_t* vp_ = vloc + (size_t)((p) * 8 * NH) * 1024; \
;         _Pragma("unroll") for (int df = 0; df < 8; ++df) va[buf][df] = *(const bf16x8*)(vp_ + df * 128); } while (0)
; template <bool LOCAL>
; __device__ __forceinline__ void attn_unit(const bf16_t* Q, const bf16_t* KT, const bf16_t* VT, bf16_t* O, LAS unsigned char* lds, int b, int h, int r, int w, int tq, int lane) {
;     ...
;     if (LOCAL) {
;         const bf16_t* vloc = VT + ((size_t)(((rgl >> 3) + g) * NH + h)) * 1024 + q * 8;
;         bf16x8 va[2][8];
;     ...
;         ATT_VLOAD(0, 0);
; #pragma unroll
;         for (int p = 0; p < 8; ++p) {
;             __builtin_amdgcn_s_barrier();
;             if (p + 1 < 8) ATT_VLOAD((p + 1) & 1, p + 1);
;             __builtin_amdgcn_sched_barrier(0);
; #pragma unroll
;             for (int df = 0; df < 8; ++df) o[df] = __builtin_amdgcn_mfma_f32_16x16x32_bf16(va[p & 1][df], pb[p], o[df], 0, 0, 0);
;             __builtin_amdgcn_sched_barrier(0);
;         }
.Lring_v_B:
	s_waitcnt vmcnt(1)
	s_barrier
	s_add_i32 m0, s59, 16384
	v_add_co_u32_e32 v222, vcc, s6, v220
	s_nop 1
	v_addc_co_u32_e32 v223, vcc, 0, v221, vcc
	global_load_lds_dwordx4 v[222:223], off
	s_waitcnt vmcnt(1)
	s_barrier
	s_add_i32 m0, s59, -1024
	v_add_co_u32_e32 v222, vcc, s6, v220
	s_nop 1
	v_addc_co_u32_e32 v223, vcc, 0, v221, vcc
	global_load_lds_dwordx4 v[222:223], off offset:1024
	s_waitcnt vmcnt(1)
	s_barrier
	s_add_i32 m0, s59, 8192
	v_add_co_u32_e32 v222, vcc, s7, v220
	s_nop 1
	v_addc_co_u32_e32 v223, vcc, 0, v221, vcc
	global_load_lds_dwordx4 v[222:223], off
	ds_read_b128 v[106:109], v219 offset:16384
	ds_read_b128 v[110:113], v219 offset:16640
	ds_read_b128 v[114:117], v219 offset:16896
	ds_read_b128 v[118:121], v219 offset:17152
	s_waitcnt lgkmcnt(3)
	v_mfma_f32_16x16x32_bf16 v[22:25], v[106:109], v[66:69], 0
	s_waitcnt lgkmcnt(2)
	v_mfma_f32_16x16x32_bf16 v[30:33], v[110:113], v[66:69], 0
	s_waitcnt lgkmcnt(1)
	v_mfma_f32_16x16x32_bf16 v[34:37], v[114:117], v[66:69], 0
	s_waitcnt lgkmcnt(0)
	v_mfma_f32_16x16x32_bf16 v[38:41], v[118:121], v[66:69], 0
	s_waitcnt vmcnt(1)
	s_barrier
	s_add_i32 m0, s59, 15360
	v_add_co_u32_e32 v222, vcc, s7, v220
	s_nop 1
	v_addc_co_u32_e32 v223, vcc, 0, v221, vcc
	global_load_lds_dwordx4 v[222:223], off offset:1024
	ds_read_b128 v[122:125], v219 offset:0
	ds_read_b128 v[126:129], v219 offset:256
	ds_read_b128 v[58:61], v219 offset:512
	ds_read_b128 v[62:65], v219 offset:768
	s_waitcnt lgkmcnt(3)
	v_mfma_f32_16x16x32_bf16 v[42:45], v[122:125], v[66:69], 0
	s_waitcnt lgkmcnt(2)
	v_mfma_f32_16x16x32_bf16 v[46:49], v[126:129], v[66:69], 0
	s_waitcnt lgkmcnt(1)
	v_mfma_f32_16x16x32_bf16 v[50:53], v[58:61], v[66:69], 0
	s_waitcnt lgkmcnt(0)
	v_mfma_f32_16x16x32_bf16 v[54:57], v[62:65], v[66:69], 0
	s_waitcnt vmcnt(1)
	s_barrier
	s_add_i32 m0, s59, 0
	v_add_co_u32_e32 v222, vcc, s2, v220
	s_nop 1
	v_addc_co_u32_e32 v223, vcc, 0, v221, vcc
	global_load_lds_dwordx4 v[222:223], off
	ds_read_b128 v[106:109], v219 offset:8192
	ds_read_b128 v[110:113], v219 offset:8448
	ds_read_b128 v[114:117], v219 offset:8704
	ds_read_b128 v[118:121], v219 offset:8960
	s_waitcnt lgkmcnt(3)
	v_mfma_f32_16x16x32_bf16 v[22:25], v[106:109], v[70:73], v[22:25]
	s_waitcnt lgkmcnt(2)
	v_mfma_f32_16x16x32_bf16 v[30:33], v[110:113], v[70:73], v[30:33]
	s_waitcnt lgkmcnt(1)
	v_mfma_f32_16x16x32_bf16 v[34:37], v[114:117], v[70:73], v[34:37]
	s_waitcnt lgkmcnt(0)
	v_mfma_f32_16x16x32_bf16 v[38:41], v[118:121], v[70:73], v[38:41]
	s_waitcnt vmcnt(1)
	s_barrier
	s_add_i32 m0, s59, 7168
	v_add_co_u32_e32 v222, vcc, s2, v220
	s_nop 1
	v_addc_co_u32_e32 v223, vcc, 0, v221, vcc
	global_load_lds_dwordx4 v[222:223], off offset:1024
	ds_read_b128 v[122:125], v219 offset:16384
	ds_read_b128 v[126:129], v219 offset:16640
	ds_read_b128 v[58:61], v219 offset:16896
	ds_read_b128 v[62:65], v219 offset:17152
	s_waitcnt lgkmcnt(3)
	v_mfma_f32_16x16x32_bf16 v[42:45], v[122:125], v[70:73], v[42:45]
	s_waitcnt lgkmcnt(2)
	v_mfma_f32_16x16x32_bf16 v[46:49], v[126:129], v[70:73], v[46:49]
	s_waitcnt lgkmcnt(1)
	v_mfma_f32_16x16x32_bf16 v[50:53], v[58:61], v[70:73], v[50:53]
	s_waitcnt lgkmcnt(0)
	v_mfma_f32_16x16x32_bf16 v[54:57], v[62:65], v[70:73], v[54:57]
	s_waitcnt vmcnt(1)
	s_barrier
	s_add_i32 m0, s59, 16384
	v_add_co_u32_e32 v222, vcc, s60, v220
	s_nop 1
	v_addc_co_u32_e32 v223, vcc, 0, v221, vcc
	global_load_lds_dwordx4 v[222:223], off
	ds_read_b128 v[106:109], v219 offset:0
	ds_read_b128 v[110:113], v219 offset:256
	ds_read_b128 v[114:117], v219 offset:512
	ds_read_b128 v[118:121], v219 offset:768
	s_waitcnt lgkmcnt(3)
	v_mfma_f32_16x16x32_bf16 v[22:25], v[106:109], v[74:77], v[22:25]
	s_waitcnt lgkmcnt(2)
	v_mfma_f32_16x16x32_bf16 v[30:33], v[110:113], v[74:77], v[30:33]
	s_waitcnt lgkmcnt(1)
	v_mfma_f32_16x16x32_bf16 v[34:37], v[114:117], v[74:77], v[34:37]
	s_waitcnt lgkmcnt(0)
	v_mfma_f32_16x16x32_bf16 v[38:41], v[118:121], v[74:77], v[38:41]
	s_waitcnt vmcnt(1)
	s_barrier
	s_add_i32 m0, s59, -1024
	v_add_co_u32_e32 v222, vcc, s60, v220
	s_nop 1
	v_addc_co_u32_e32 v223, vcc, 0, v221, vcc
	global_load_lds_dwordx4 v[222:223], off offset:1024
	ds_read_b128 v[122:125], v219 offset:8192
	ds_read_b128 v[126:129], v219 offset:8448
	ds_read_b128 v[58:61], v219 offset:8704
	ds_read_b128 v[62:65], v219 offset:8960
	s_waitcnt lgkmcnt(3)
	v_mfma_f32_16x16x32_bf16 v[42:45], v[122:125], v[74:77], v[42:45]
	s_waitcnt lgkmcnt(2)
	v_mfma_f32_16x16x32_bf16 v[46:49], v[126:129], v[74:77], v[46:49]
	s_waitcnt lgkmcnt(1)
	v_mfma_f32_16x16x32_bf16 v[50:53], v[58:61], v[74:77], v[50:53]
	s_waitcnt lgkmcnt(0)
	v_mfma_f32_16x16x32_bf16 v[54:57], v[62:65], v[74:77], v[54:57]
	s_waitcnt vmcnt(1)
	s_barrier
; #define ATT_VLOAD(buf, p) do { const bf16_t* vp_ = vloc + (size_t)((p) * 8 * NH) * 1024; \
;         _Pragma("unroll") for (int df = 0; df < 8; ++df) va[buf][df] = *(const bf16x8*)(vp_ + df * 128); } while (0)
; template <bool LOCAL>
; __device__ __forceinline__ void attn_unit(const bf16_t* Q, const bf16_t* KT, const bf16_t* VT, bf16_t* O, LAS unsigned char* lds, int b, int h, int r, int w, int tq, int lane) {
;     ...
;     if (LOCAL) {
;         const bf16_t* vloc = VT + ((size_t)(((rgl >> 3) + g) * NH + h)) * 1024 + q * 8;
;         bf16x8 va[2][8];
;     ...
;         ATT_VLOAD(0, 0);
; #pragma unroll
;         for (int p = 0; p < 8; ++p) {
;             __builtin_amdgcn_s_barrier();
;             if (p + 1 < 8) ATT_VLOAD((p + 1) & 1, p + 1);
;             __builtin_amdgcn_sched_barrier(0);
; #pragma unroll
;             for (int df = 0; df < 8; ++df) o[df] = __builtin_amdgcn_mfma_f32_16x16x32_bf16(va[p & 1][df], pb[p], o[df], 0, 0, 0);
;             __builtin_amdgcn_sched_barrier(0);
;         }
	s_add_i32 m0, s59, 8192
	v_add_co_u32_e32 v222, vcc, s61, v220
	s_nop 1
	v_addc_co_u32_e32 v223, vcc, 0, v221, vcc
	global_load_lds_dwordx4 v[222:223], off
	ds_read_b128 v[106:109], v219 offset:16384
	ds_read_b128 v[110:113], v219 offset:16640
	ds_read_b128 v[114:117], v219 offset:16896
	ds_read_b128 v[118:121], v219 offset:17152
	s_waitcnt lgkmcnt(3)
	v_mfma_f32_16x16x32_bf16 v[22:25], v[106:109], v[78:81], v[22:25]
	s_waitcnt lgkmcnt(2)
	v_mfma_f32_16x16x32_bf16 v[30:33], v[110:113], v[78:81], v[30:33]
	s_waitcnt lgkmcnt(1)
	v_mfma_f32_16x16x32_bf16 v[34:37], v[114:117], v[78:81], v[34:37]
	s_waitcnt lgkmcnt(0)
	v_mfma_f32_16x16x32_bf16 v[38:41], v[118:121], v[78:81], v[38:41]
	s_waitcnt vmcnt(1)
	s_barrier
	s_add_i32 m0, s59, 15360
	v_add_co_u32_e32 v222, vcc, s61, v220
	s_nop 1
	v_addc_co_u32_e32 v223, vcc, 0, v221, vcc
	global_load_lds_dwordx4 v[222:223], off offset:1024
	ds_read_b128 v[122:125], v219 offset:0
	ds_read_b128 v[126:129], v219 offset:256
	ds_read_b128 v[58:61], v219 offset:512
	ds_read_b128 v[62:65], v219 offset:768
	s_waitcnt lgkmcnt(3)
	v_mfma_f32_16x16x32_bf16 v[42:45], v[122:125], v[78:81], v[42:45]
	s_waitcnt lgkmcnt(2)
	v_mfma_f32_16x16x32_bf16 v[46:49], v[126:129], v[78:81], v[46:49]
	s_waitcnt lgkmcnt(1)
	v_mfma_f32_16x16x32_bf16 v[50:53], v[58:61], v[78:81], v[50:53]
	s_waitcnt lgkmcnt(0)
	v_mfma_f32_16x16x32_bf16 v[54:57], v[62:65], v[78:81], v[54:57]
	s_waitcnt vmcnt(1)
	s_barrier
	s_add_i32 m0, s59, 0
	v_add_co_u32_e32 v222, vcc, s17, v220
	s_nop 1
	v_addc_co_u32_e32 v223, vcc, 0, v221, vcc
	global_load_lds_dwordx4 v[222:223], off
	ds_read_b128 v[106:109], v219 offset:8192
	ds_read_b128 v[110:113], v219 offset:8448
	ds_read_b128 v[114:117], v219 offset:8704
	ds_read_b128 v[118:121], v219 offset:8960
	s_waitcnt lgkmcnt(3)
	v_mfma_f32_16x16x32_bf16 v[22:25], v[106:109], v[82:85], v[22:25]
	s_waitcnt lgkmcnt(2)
	v_mfma_f32_16x16x32_bf16 v[30:33], v[110:113], v[82:85], v[30:33]
	s_waitcnt lgkmcnt(1)
	v_mfma_f32_16x16x32_bf16 v[34:37], v[114:117], v[82:85], v[34:37]
	s_waitcnt lgkmcnt(0)
	v_mfma_f32_16x16x32_bf16 v[38:41], v[118:121], v[82:85], v[38:41]
	s_waitcnt vmcnt(1)
	s_barrier
	s_add_i32 m0, s59, 7168
	v_add_co_u32_e32 v222, vcc, s17, v220
	s_nop 1
	v_addc_co_u32_e32 v223, vcc, 0, v221, vcc
	global_load_lds_dwordx4 v[222:223], off offset:1024
	ds_read_b128 v[122:125], v219 offset:16384
	ds_read_b128 v[126:129], v219 offset:16640
	ds_read_b128 v[58:61], v219 offset:16896
	ds_read_b128 v[62:65], v219 offset:17152
	s_waitcnt lgkmcnt(3)
	v_mfma_f32_16x16x32_bf16 v[42:45], v[122:125], v[82:85], v[42:45]
	s_waitcnt lgkmcnt(2)
	v_mfma_f32_16x16x32_bf16 v[46:49], v[126:129], v[82:85], v[46:49]
	s_waitcnt lgkmcnt(1)
	v_mfma_f32_16x16x32_bf16 v[50:53], v[58:61], v[82:85], v[50:53]
	s_waitcnt lgkmcnt(0)
	v_mfma_f32_16x16x32_bf16 v[54:57], v[62:65], v[82:85], v[54:57]
	s_waitcnt vmcnt(1)
	s_barrier
	s_add_i32 m0, s59, 16384
	v_add_co_u32_e32 v222, vcc, s62, v220
	s_nop 1
	v_addc_co_u32_e32 v223, vcc, 0, v221, vcc
	global_load_lds_dwordx4 v[222:223], off
	ds_read_b128 v[106:109], v219 offset:0
	ds_read_b128 v[110:113], v219 offset:256
	ds_read_b128 v[114:117], v219 offset:512
	ds_read_b128 v[118:121], v219 offset:768
	s_waitcnt lgkmcnt(3)
	v_mfma_f32_16x16x32_bf16 v[22:25], v[106:109], v[86:89], v[22:25]
	s_waitcnt lgkmcnt(2)
	v_mfma_f32_16x16x32_bf16 v[30:33], v[110:113], v[86:89], v[30:33]
	s_waitcnt lgkmcnt(1)
	v_mfma_f32_16x16x32_bf16 v[34:37], v[114:117], v[86:89], v[34:37]
	s_waitcnt lgkmcnt(0)
	v_mfma_f32_16x16x32_bf16 v[38:41], v[118:121], v[86:89], v[38:41]
	s_waitcnt vmcnt(1)
	s_barrier
	s_add_i32 m0, s59, -1024
	v_add_co_u32_e32 v222, vcc, s62, v220
	s_nop 1
	v_addc_co_u32_e32 v223, vcc, 0, v221, vcc
	global_load_lds_dwordx4 v[222:223], off offset:1024
	ds_read_b128 v[122:125], v219 offset:8192
	ds_read_b128 v[126:129], v219 offset:8448
	ds_read_b128 v[58:61], v219 offset:8704
	ds_read_b128 v[62:65], v219 offset:8960
	s_waitcnt lgkmcnt(3)
	v_mfma_f32_16x16x32_bf16 v[42:45], v[122:125], v[86:89], v[42:45]
	s_waitcnt lgkmcnt(2)
	v_mfma_f32_16x16x32_bf16 v[46:49], v[126:129], v[86:89], v[46:49]
	s_waitcnt lgkmcnt(1)
	v_mfma_f32_16x16x32_bf16 v[50:53], v[58:61], v[86:89], v[50:53]
	s_waitcnt lgkmcnt(0)
	v_mfma_f32_16x16x32_bf16 v[54:57], v[62:65], v[86:89], v[54:57]
	s_waitcnt vmcnt(1)
	s_barrier
	s_cmp_eq_u32 s73, 0
	s_cbranch_scc1 .Lring_v_B_nd14
	s_add_i32 m0, s59, 8192
	v_add_co_u32_e32 v222, vcc, s75, v220
	s_nop 1
	v_addc_co_u32_e32 v223, vcc, 0, v221, vcc
	global_load_lds_dwordx4 v[222:223], off
.Lring_v_B_nd14:
	ds_read_b128 v[106:109], v219 offset:16384
	ds_read_b128 v[110:113], v219 offset:16640
	ds_read_b128 v[114:117], v219 offset:16896
	ds_read_b128 v[118:121], v219 offset:17152
	s_waitcnt lgkmcnt(3)
	v_mfma_f32_16x16x32_bf16 v[22:25], v[106:109], v[94:97], v[22:25]
	s_waitcnt lgkmcnt(2)
	v_mfma_f32_16x16x32_bf16 v[30:33], v[110:113], v[94:97], v[30:33]
	s_waitcnt lgkmcnt(1)
	v_mfma_f32_16x16x32_bf16 v[34:37], v[114:117], v[94:97], v[34:37]
	s_waitcnt lgkmcnt(0)
	v_mfma_f32_16x16x32_bf16 v[38:41], v[118:121], v[94:97], v[38:41]
	s_cmp_eq_u32 s73, 0
	s_cbranch_scc1 .Lring_v_B_w15
	s_waitcnt vmcnt(1)
	s_branch .Lring_v_B_b15

; #define LAS __attribute__((address_space(3)))
; #define ATT_VLOAD(buf, p) do { const bf16_t* vp_ = vloc + (size_t)((p) * 8 * NH) * 1024; \
;         _Pragma("unroll") for (int df = 0; df < 8; ++df) va[buf][df] = *(const bf16x8*)(vp_ + df * 128); } while (0)
; template <bool LOCAL>
; __device__ __forceinline__ void attn_unit(const bf16_t* Q, const bf16_t* KT, const bf16_t* VT, bf16_t* O, LAS unsigned char* lds, int b, int h, int r, int w, int tq, int lane) {
;     ...
;     if (LOCAL) {
;         const bf16_t* vloc = VT + ((size_t)(((rgl >> 3) + g) * NH + h)) * 1024 + q * 8;
;         bf16x8 va[2][8];
;     ...
;         ATT_VLOAD(0, 0);
; #pragma unroll
;         for (int p = 0; p < 8; ++p) {
;             __builtin_amdgcn_s_barrier();
;             if (p + 1 < 8) ATT_VLOAD((p + 1) & 1, p + 1);
;             __builtin_amdgcn_sched_barrier(0);
; #pragma unroll
;             for (int df = 0; df < 8; ++df) o[df] = __builtin_amdgcn_mfma_f32_16x16x32_bf16(va[p & 1][df], pb[p], o[df], 0, 0, 0);
;             __builtin_amdgcn_sched_barrier(0);
;         }
;     ...
;     {
;         const LAS unsigned char* vl = lds + 65536 + g * 2048 + q * 16;
; #pragma unroll
;         for (int p = 0; p < 8; ++p)
; #pragma unroll
;             for (int df = 0; df < 8; ++df) o[df] = __builtin_amdgcn_mfma_f32_16x16x32_bf16(*(const LAS bf16x8*)(vl + p * 8192 + df * 256), pb[CP + p], o[df], 0, 0, 0);
;     }
.Lring_v_B_nd15:
	ds_read_b128 v[122:125], v219 offset:0
	ds_read_b128 v[126:129], v219 offset:256
	ds_read_b128 v[58:61], v219 offset:512
	ds_read_b128 v[62:65], v219 offset:768
	s_waitcnt lgkmcnt(3)
	v_mfma_f32_16x16x32_bf16 v[42:45], v[122:125], v[94:97], v[42:45]
	s_waitcnt lgkmcnt(2)
	v_mfma_f32_16x16x32_bf16 v[46:49], v[126:129], v[94:97], v[46:49]
	s_waitcnt lgkmcnt(1)
	v_mfma_f32_16x16x32_bf16 v[50:53], v[58:61], v[94:97], v[50:53]
	s_waitcnt lgkmcnt(0)
	v_mfma_f32_16x16x32_bf16 v[54:57], v[62:65], v[94:97], v[54:57]
	s_cmp_eq_u32 s73, 0
	s_cbranch_scc1 .Lring_v_B_end
	s_waitcnt vmcnt(1)
	s_barrier
	ds_read_b128 v[106:109], v219 offset:8192
	ds_read_b128 v[110:113], v219 offset:8448
	ds_read_b128 v[114:117], v219 offset:8704
	ds_read_b128 v[118:121], v219 offset:8960
	s_waitcnt lgkmcnt(3)
	v_mfma_f32_16x16x32_bf16 v[22:25], v[106:109], v[102:105], v[22:25]
	s_waitcnt lgkmcnt(2)
	v_mfma_f32_16x16x32_bf16 v[30:33], v[110:113], v[102:105], v[30:33]
	s_waitcnt lgkmcnt(1)
	v_mfma_f32_16x16x32_bf16 v[34:37], v[114:117], v[102:105], v[34:37]
	s_waitcnt lgkmcnt(0)
	v_mfma_f32_16x16x32_bf16 v[38:41], v[118:121], v[102:105], v[38:41]
	s_waitcnt vmcnt(0)
	s_barrier
	ds_read_b128 v[122:125], v219 offset:16384
	ds_read_b128 v[126:129], v219 offset:16640
	ds_read_b128 v[58:61], v219 offset:16896
	ds_read_b128 v[62:65], v219 offset:17152
	s_waitcnt lgkmcnt(3)
	v_mfma_f32_16x16x32_bf16 v[42:45], v[122:125], v[102:105], v[42:45]
	s_waitcnt lgkmcnt(2)
	v_mfma_f32_16x16x32_bf16 v[46:49], v[126:129], v[102:105], v[46:49]
	s_waitcnt lgkmcnt(1)
	v_mfma_f32_16x16x32_bf16 v[50:53], v[58:61], v[102:105], v[50:53]
	s_waitcnt lgkmcnt(0)
	v_mfma_f32_16x16x32_bf16 v[54:57], v[62:65], v[102:105], v[54:57]
.Lring_v_B_end:
.Lring_v_done:
	s_waitcnt lgkmcnt(0)
	s_add_i32 s48, s48, 2
	s_add_i32 s52, s52, 2
	s_add_i32 s51, s51, -2
	v_add_u32_e32 v162, 0x80, v162
	s_cmp_eq_u32 s48, 8
	ds_read_b128 v[208:211], v178
	ds_read_b128 v[212:215], v178 offset:256
	ds_read_b128 v[216:219], v178 offset:512
	ds_read_b128 v[220:223], v178 offset:768
	ds_read_b128 v[224:227], v178 offset:1024
	ds_read_b128 v[228:231], v178 offset:1280
	ds_read_b128 v[232:235], v178 offset:1536
	ds_read_b128 v[246:249], v178 offset:1792
	s_waitcnt lgkmcnt(7)
	v_mfma_f32_16x16x32_bf16 v[22:25], v[208:211], v[98:101], v[22:25]
	ds_read_b128 v[208:211], v178 offset:8192
	s_waitcnt lgkmcnt(7)
	v_mfma_f32_16x16x32_bf16 v[30:33], v[212:215], v[98:101], v[30:33]
	ds_read_b128 v[212:215], v178 offset:8448
	s_waitcnt lgkmcnt(7)
	v_mfma_f32_16x16x32_bf16 v[34:37], v[216:219], v[98:101], v[34:37]
	ds_read_b128 v[216:219], v178 offset:8704
	s_waitcnt lgkmcnt(7)
	v_mfma_f32_16x16x32_bf16 v[38:41], v[220:223], v[98:101], v[38:41]
	ds_read_b128 v[220:223], v178 offset:8960
	s_waitcnt lgkmcnt(7)
	v_mfma_f32_16x16x32_bf16 v[42:45], v[224:227], v[98:101], v[42:45]
	ds_read_b128 v[224:227], v178 offset:9216
	s_waitcnt lgkmcnt(7)
	v_mfma_f32_16x16x32_bf16 v[46:49], v[228:231], v[98:101], v[46:49]
	ds_read_b128 v[228:231], v178 offset:9472
	s_waitcnt lgkmcnt(7)
	v_mfma_f32_16x16x32_bf16 v[50:53], v[232:235], v[98:101], v[50:53]
	ds_read_b128 v[232:235], v178 offset:9728
	s_waitcnt lgkmcnt(7)
	v_mfma_f32_16x16x32_bf16 v[54:57], v[246:249], v[98:101], v[54:57]
	ds_read_b128 v[246:249], v178 offset:9984
	s_waitcnt lgkmcnt(7)
	v_mfma_f32_16x16x32_bf16 v[22:25], v[208:211], v[90:93], v[22:25]
	ds_read_b128 v[208:211], v178 offset:16384
	s_waitcnt lgkmcnt(7)
	v_mfma_f32_16x16x32_bf16 v[30:33], v[212:215], v[90:93], v[30:33]
	ds_read_b128 v[212:215], v178 offset:16640
	s_waitcnt lgkmcnt(7)
	v_mfma_f32_16x16x32_bf16 v[34:37], v[216:219], v[90:93], v[34:37]
	ds_read_b128 v[216:219], v178 offset:16896
	s_waitcnt lgkmcnt(7)
	v_mfma_f32_16x16x32_bf16 v[38:41], v[220:223], v[90:93], v[38:41]
	ds_read_b128 v[220:223], v178 offset:17152
	s_waitcnt lgkmcnt(7)
	v_mfma_f32_16x16x32_bf16 v[42:45], v[224:227], v[90:93], v[42:45]
	ds_read_b128 v[224:227], v178 offset:17408
	s_waitcnt lgkmcnt(7)
	v_mfma_f32_16x16x32_bf16 v[46:49], v[228:231], v[90:93], v[46:49]
	ds_read_b128 v[228:231], v178 offset:17664
	s_waitcnt lgkmcnt(7)
	v_mfma_f32_16x16x32_bf16 v[50:53], v[232:235], v[90:93], v[50:53]
	ds_read_b128 v[232:235], v178 offset:17920
	s_waitcnt lgkmcnt(7)
	v_mfma_f32_16x16x32_bf16 v[54:57], v[246:249], v[90:93], v[54:57]
	ds_read_b128 v[246:249], v178 offset:18176
	s_waitcnt lgkmcnt(7)
	v_mfma_f32_16x16x32_bf16 v[22:25], v[208:211], v[26:29], v[22:25]
	ds_read_b128 v[208:211], v178 offset:24576
	s_waitcnt lgkmcnt(7)
	v_mfma_f32_16x16x32_bf16 v[30:33], v[212:215], v[26:29], v[30:33]
	ds_read_b128 v[212:215], v178 offset:24832
	s_waitcnt lgkmcnt(7)
	v_mfma_f32_16x16x32_bf16 v[34:37], v[216:219], v[26:29], v[34:37]
	ds_read_b128 v[216:219], v178 offset:25088
	s_waitcnt lgkmcnt(7)
	v_mfma_f32_16x16x32_bf16 v[38:41], v[220:223], v[26:29], v[38:41]
	ds_read_b128 v[220:223], v178 offset:25344
	s_waitcnt lgkmcnt(7)
	v_mfma_f32_16x16x32_bf16 v[42:45], v[224:227], v[26:29], v[42:45]
	ds_read_b128 v[224:227], v178 offset:25600
	s_waitcnt lgkmcnt(7)
	v_mfma_f32_16x16x32_bf16 v[46:49], v[228:231], v[26:29], v[46:49]
	ds_read_b128 v[228:231], v178 offset:25856
	s_waitcnt lgkmcnt(7)
	v_mfma_f32_16x16x32_bf16 v[50:53], v[232:235], v[26:29], v[50:53]
	ds_read_b128 v[232:235], v178 offset:26112
	s_waitcnt lgkmcnt(7)
	v_mfma_f32_16x16x32_bf16 v[26:29], v[246:249], v[26:29], v[54:57]
	ds_read_b128 v[246:249], v178 offset:26368
	s_waitcnt lgkmcnt(7)
	v_mfma_f32_16x16x32_bf16 v[22:25], v[208:211], v[10:13], v[22:25]
	ds_read_b128 v[208:211], v178 offset:32768
	s_waitcnt lgkmcnt(7)
	v_mfma_f32_16x16x32_bf16 v[30:33], v[212:215], v[10:13], v[30:33]
	ds_read_b128 v[212:215], v178 offset:33024
	s_waitcnt lgkmcnt(7)
; #define LAS __attribute__((address_space(3)))
; __device__ __forceinline__ unsigned cvt_pk_bf16(float lo, float hi) { unsigned r; asm volatile("v_cvt_pk_bf16_f32 %0, %1, %2" : "=v"(r) : "v"(lo), "v"(hi)); return r; }
; template <bool LOCAL>
; __device__ __forceinline__ void attn_unit(const bf16_t* Q, const bf16_t* KT, const bf16_t* VT, bf16_t* O, LAS unsigned char* lds, int b, int h, int r, int w, int tq, int lane) {
;     ...
;     {
;         const LAS unsigned char* vl = lds + 65536 + g * 2048 + q * 16;
; #pragma unroll
;         for (int p = 0; p < 8; ++p)
; #pragma unroll
;             for (int df = 0; df < 8; ++df) o[df] = __builtin_amdgcn_mfma_f32_16x16x32_bf16(*(const LAS bf16x8*)(vl + p * 8192 + df * 256), pb[CP + p], o[df], 0, 0, 0);
;     }
;     const float inv = 1.f / sum;
;     bf16_t* op = O + (size_t)qrow * D + h * HD + 4 * g;
; #pragma unroll
;     for (int df = 0; df < 8; ++df) { u32x2 wv; wv.x = cvt_pk_bf16(o[df][0] * inv, o[df][1] * inv); wv.y = cvt_pk_bf16(o[df][2] * inv, o[df][3] * inv); *(u32x2*)(op + 16 * df) = wv; }
; }
	v_mfma_f32_16x16x32_bf16 v[34:37], v[216:219], v[10:13], v[34:37]
	ds_read_b128 v[216:219], v178 offset:33280
	s_waitcnt lgkmcnt(7)
	v_mfma_f32_16x16x32_bf16 v[38:41], v[220:223], v[10:13], v[38:41]
	ds_read_b128 v[220:223], v178 offset:33536
	s_waitcnt lgkmcnt(7)
	v_mfma_f32_16x16x32_bf16 v[42:45], v[224:227], v[10:13], v[42:45]
	ds_read_b128 v[224:227], v178 offset:33792
	s_waitcnt lgkmcnt(7)
	v_mfma_f32_16x16x32_bf16 v[46:49], v[228:231], v[10:13], v[46:49]
	ds_read_b128 v[228:231], v178 offset:34048
	s_waitcnt lgkmcnt(7)
	v_mfma_f32_16x16x32_bf16 v[50:53], v[232:235], v[10:13], v[50:53]
	ds_read_b128 v[232:235], v178 offset:34304
	s_waitcnt lgkmcnt(7)
	v_mfma_f32_16x16x32_bf16 v[10:13], v[246:249], v[10:13], v[26:29]
	ds_read_b128 v[246:249], v178 offset:34560
	s_waitcnt lgkmcnt(7)
	v_mfma_f32_16x16x32_bf16 v[22:25], v[208:211], v[2:5], v[22:25]
	ds_read_b128 v[208:211], v178 offset:40960
	s_waitcnt lgkmcnt(7)
	v_mfma_f32_16x16x32_bf16 v[26:29], v[212:215], v[2:5], v[30:33]
	ds_read_b128 v[212:215], v178 offset:41216
	s_waitcnt lgkmcnt(7)
	v_mfma_f32_16x16x32_bf16 v[30:33], v[216:219], v[2:5], v[34:37]
	ds_read_b128 v[216:219], v178 offset:41472
	s_waitcnt lgkmcnt(7)
	v_mfma_f32_16x16x32_bf16 v[34:37], v[220:223], v[2:5], v[38:41]
	ds_read_b128 v[220:223], v178 offset:41728
	s_waitcnt lgkmcnt(7)
	v_mfma_f32_16x16x32_bf16 v[38:41], v[224:227], v[2:5], v[42:45]
	ds_read_b128 v[224:227], v178 offset:41984
	s_waitcnt lgkmcnt(7)
	v_mfma_f32_16x16x32_bf16 v[42:45], v[228:231], v[2:5], v[46:49]
	ds_read_b128 v[228:231], v178 offset:42240
	s_waitcnt lgkmcnt(7)
	v_mfma_f32_16x16x32_bf16 v[46:49], v[232:235], v[2:5], v[50:53]
	ds_read_b128 v[232:235], v178 offset:42496
	s_waitcnt lgkmcnt(7)
	v_mfma_f32_16x16x32_bf16 v[2:5], v[246:249], v[2:5], v[10:13]
	ds_read_b128 v[246:249], v178 offset:42752
	s_waitcnt lgkmcnt(7)
	v_mfma_f32_16x16x32_bf16 v[10:13], v[208:211], v[6:9], v[22:25]
	ds_read_b128 v[208:211], v178 offset:49152
	s_waitcnt lgkmcnt(7)
	v_mfma_f32_16x16x32_bf16 v[22:25], v[212:215], v[6:9], v[26:29]
	ds_read_b128 v[212:215], v178 offset:49408
	s_waitcnt lgkmcnt(7)
	v_mfma_f32_16x16x32_bf16 v[26:29], v[216:219], v[6:9], v[30:33]
	ds_read_b128 v[216:219], v178 offset:49664
	s_waitcnt lgkmcnt(7)
	v_mfma_f32_16x16x32_bf16 v[30:33], v[220:223], v[6:9], v[34:37]
	ds_read_b128 v[220:223], v178 offset:49920
	s_waitcnt lgkmcnt(7)
	v_mfma_f32_16x16x32_bf16 v[34:37], v[224:227], v[6:9], v[38:41]
	ds_read_b128 v[224:227], v178 offset:50176
	s_waitcnt lgkmcnt(7)
	v_mfma_f32_16x16x32_bf16 v[38:41], v[228:231], v[6:9], v[42:45]
	ds_read_b128 v[228:231], v178 offset:50432
	s_waitcnt lgkmcnt(7)
	v_mfma_f32_16x16x32_bf16 v[42:45], v[232:235], v[6:9], v[46:49]
	ds_read_b128 v[232:235], v178 offset:50688
	s_waitcnt lgkmcnt(7)
	v_mfma_f32_16x16x32_bf16 v[2:5], v[246:249], v[6:9], v[2:5]
	ds_read_b128 v[246:249], v178 offset:50944
	s_waitcnt lgkmcnt(7)
	v_mfma_f32_16x16x32_bf16 v[6:9], v[208:211], v[14:17], v[10:13]
	ds_read_b128 v[208:211], v178 offset:57344
	s_waitcnt lgkmcnt(7)
	v_mfma_f32_16x16x32_bf16 v[10:13], v[212:215], v[14:17], v[22:25]
	ds_read_b128 v[212:215], v178 offset:57600
	s_waitcnt lgkmcnt(7)
	v_mfma_f32_16x16x32_bf16 v[22:25], v[216:219], v[14:17], v[26:29]
	ds_read_b128 v[216:219], v178 offset:57856
	s_waitcnt lgkmcnt(7)
	v_mfma_f32_16x16x32_bf16 v[26:29], v[220:223], v[14:17], v[30:33]
	ds_read_b128 v[220:223], v178 offset:58112
	s_waitcnt lgkmcnt(7)
	v_mfma_f32_16x16x32_bf16 v[30:33], v[224:227], v[14:17], v[34:37]
	ds_read_b128 v[224:227], v178 offset:58368
	s_waitcnt lgkmcnt(7)
	v_mfma_f32_16x16x32_bf16 v[34:37], v[228:231], v[14:17], v[38:41]
	ds_read_b128 v[228:231], v178 offset:58624
	s_waitcnt lgkmcnt(7)
	v_mfma_f32_16x16x32_bf16 v[38:41], v[232:235], v[14:17], v[42:45]
	ds_read_b128 v[232:235], v178 offset:58880
	s_waitcnt lgkmcnt(7)
	v_mfma_f32_16x16x32_bf16 v[2:5], v[246:249], v[14:17], v[2:5]
	ds_read_b128 v[246:249], v178 offset:59136
	s_waitcnt lgkmcnt(7)
	v_mfma_f32_16x16x32_bf16 v[6:9], v[208:211], v[18:21], v[6:9]
	s_waitcnt lgkmcnt(6)
	v_mfma_f32_16x16x32_bf16 v[10:13], v[212:215], v[18:21], v[10:13]
	s_waitcnt lgkmcnt(5)
	v_mfma_f32_16x16x32_bf16 v[14:17], v[216:219], v[18:21], v[22:25]
	s_waitcnt lgkmcnt(4)
	v_mfma_f32_16x16x32_bf16 v[22:25], v[220:223], v[18:21], v[26:29]
	s_waitcnt lgkmcnt(3)
	v_mfma_f32_16x16x32_bf16 v[26:29], v[224:227], v[18:21], v[30:33]
	s_waitcnt lgkmcnt(2)
	v_mfma_f32_16x16x32_bf16 v[30:33], v[228:231], v[18:21], v[34:37]
	s_waitcnt lgkmcnt(1)
	v_mfma_f32_16x16x32_bf16 v[34:37], v[232:235], v[18:21], v[38:41]
	s_waitcnt lgkmcnt(0)
	v_mfma_f32_16x16x32_bf16 v[2:5], v[246:249], v[18:21], v[2:5]
	s_nop 7
	v_add_f32_e32 v18, v134, v135
	v_div_scale_f32 v19, s[4:5], v18, v18, 1.0
	v_rcp_f32_e32 v20, v19
	s_nop 0
	v_fma_f32 v21, -v19, v20, 1.0
	v_fmac_f32_e32 v20, v21, v20
	v_div_scale_f32 v21, vcc, 1.0, v18, 1.0
	v_mul_f32_e32 v38, v21, v20
	v_fma_f32 v39, -v19, v38, v21
	v_fmac_f32_e32 v38, v39, v20
	v_fma_f32 v19, -v19, v38, v21
	v_div_fmas_f32 v19, v19, v20, v38
	v_div_fixup_f32 v20, v19, v18, 1.0
	v_mul_f32_e32 v6, v20, v6
	v_mul_f32_e32 v7, v20, v7
	v_cvt_pk_bf16_f32 v6, v6, v7
	v_mul_f32_e32 v7, v20, v8
	v_lshl_add_u64 v[18:19], v[130:131], 1, v[160:161]
	v_mul_f32_e32 v8, v20, v9
	v_cvt_pk_bf16_f32 v7, v7, v8
	global_store_dwordx2 v[18:19], v[6:7], off
	v_mul_f32_e32 v6, v20, v10
	v_mul_f32_e32 v7, v20, v11
	v_cvt_pk_bf16_f32 v6, v6, v7
	v_mul_f32_e32 v7, v20, v12
	v_mul_f32_e32 v8, v20, v13
	v_cvt_pk_bf16_f32 v7, v7, v8
	global_store_dwordx2 v[18:19], v[6:7], off offset:32
	v_mul_f32_e32 v6, v20, v14
	v_mul_f32_e32 v7, v20, v15
	v_cvt_pk_bf16_f32 v6, v6, v7
	v_mul_f32_e32 v7, v20, v16
	v_mul_f32_e32 v8, v20, v17
	v_cvt_pk_bf16_f32 v7, v7, v8
	global_store_dwordx2 v[18:19], v[6:7], off offset:64
	v_mul_f32_e32 v6, v20, v22
	v_mul_f32_e32 v7, v20, v23
	v_cvt_pk_bf16_f32 v6, v6, v7
	v_mul_f32_e32 v7, v20, v24
	v_mul_f32_e32 v8, v20, v25
	v_cvt_pk_bf16_f32 v7, v7, v8
	global_store_dwordx2 v[18:19], v[6:7], off offset:96
	v_mul_f32_e32 v6, v20, v26
	v_mul_f32_e32 v7, v20, v27
	v_cvt_pk_bf16_f32 v6, v6, v7
	v_mul_f32_e32 v7, v20, v28
	v_mul_f32_e32 v8, v20, v29
	v_cvt_pk_bf16_f32 v7, v7, v8
	global_store_dwordx2 v[18:19], v[6:7], off offset:128
	v_mul_f32_e32 v6, v20, v30
	v_mul_f32_e32 v7, v20, v31
	v_cvt_pk_bf16_f32 v6, v6, v7
	v_mul_f32_e32 v7, v20, v32
	v_mul_f32_e32 v8, v20, v33
	v_cvt_pk_bf16_f32 v7, v7, v8
	global_store_dwordx2 v[18:19], v[6:7], off offset:160
	v_mul_f32_e32 v6, v20, v34
	v_mul_f32_e32 v7, v20, v35
	v_cvt_pk_bf16_f32 v6, v6, v7
	v_mul_f32_e32 v7, v20, v36
	v_mul_f32_e32 v2, v20, v2
	v_mul_f32_e32 v3, v20, v3
	v_mul_f32_e32 v8, v20, v37
	v_cvt_pk_bf16_f32 v7, v7, v8
	global_store_dwordx2 v[18:19], v[6:7], off offset:192
	v_cvt_pk_bf16_f32 v2, v2, v3
	v_mul_f32_e32 v3, v20, v4
	v_mul_f32_e32 v4, v20, v5
	v_cvt_pk_bf16_f32 v3, v3, v4
	global_store_dwordx2 v[18:19], v[2:3], off offset:224
	s_cbranch_scc1 .LBB9_802
; #define ATT_KLOAD(buf, p) do { const bf16_t* kp_ = kloc + (size_t)((p) * 8 * NH) * 1024; \
;         _Pragma("unroll") for (int f = 0; f < 2; ++f) _Pragma("unroll") for (int ks = 0; ks < 4; ++ks) ka[buf][f * 4 + ks] = *(const bf16x8*)(kp_ + f * 128 + ks * 256); } while (0)
; template <bool LOCAL>
; __device__ __forceinline__ void attn_unit(const bf16_t* Q, const bf16_t* KT, const bf16_t* VT, bf16_t* O, LAS unsigned char* lds, int b, int h, int r, int w, int tq, int lane) {
;     ...
;     { const bf16_t* qp = Q + (size_t)qrow * D + h * HD + 8 * g;
; #pragma unroll
;       for (int ks = 0; ks < 4; ++ks) bq[ks] = *(const bf16x8*)(qp + 32 * ks); }
;     constexpr int NP = LOCAL ? 16 : 8, CP = LOCAL ? 8 : 0;
;     f32x4 s[2 * NP];
;     int rs = 0, ws = 0;
;     if (LOCAL) { rs = r - 4; rs = rs < 0 ? 0 : (rs > 24 ? 24 : rs); ws = 16 * w - 8; ws = ws < 0 ? 0 : (ws > 32 ? 32 : ws); }
;     const int rgl = b * SEQ + rs * GRID_W + ws;
;     if (LOCAL) {
;         const bf16_t* kloc = KT + ((size_t)(((rgl >> 3) + (q >> 2)) * NH + h)) * 1024 + (q & 3) * 32 + g * 8;
;         bf16x8 ka[2][8];
;     ...
;         ATT_KLOAD(0, 0);
; #pragma unroll
;         for (int p = 0; p < 8; ++p) {
;             __builtin_amdgcn_s_barrier();
;             if (p + 1 < 8) ATT_KLOAD((p + 1) & 1, p + 1);
;             __builtin_amdgcn_sched_barrier(0);
; #pragma unroll
;             for (int f = 0; f < 2; ++f) { f32x4 a = {0.f, 0.f, 0.f, 0.f};
; #pragma unroll
;                 for (int ks = 0; ks < 4; ++ks) a = __builtin_amdgcn_mfma_f32_16x16x32_bf16(ka[p & 1][f * 4 + ks], bq[ks], a, 0, 0, 0);
;                 s[2 * p + f] = a; }
;             __builtin_amdgcn_sched_barrier(0);
;         }
.LBB9_674:
	v_ashrrev_i32_e32 v163, 31, v162
	v_lshlrev_b64 v[2:3], 12, v[162:163]
	s_add_i32 s4, s50, s48
	v_lshl_add_u64 v[2:3], v[158:159], 0, v[2:3]
	global_load_dwordx4 v[138:141], v[2:3], off
	global_load_dwordx4 v[134:137], v[2:3], off offset:64
	global_load_dwordx4 v[130:133], v[2:3], off offset:128
	global_load_dwordx4 v[62:65], v[2:3], off offset:192
	v_med3_i32 v2, s4, 4, 28
	v_lshlrev_b32_e32 v2, 6, v2
	v_add_u32_e32 v2, v2, v157
	v_add_u32_e32 v2, 0xffffff00, v2
	v_ashrrev_i32_e32 v194, 3, v2
	v_add_u32_e32 v2, v194, v168
	v_lshl_or_b32 v2, v2, 4, s72
	v_ashrrev_i32_e32 v3, 31, v2
	v_lshlrev_b64 v[2:3], 11, v[2:3]
	v_lshl_add_u64 v[70:71], v[146:147], 0, v[2:3]
	v_med3_i32 v232, s52, 4, 28
	v_add_u32_e32 v195, s51, v232
	s_and_b32 s54, s70, 3
	s_lshl_b32 s54, s54, 3
	s_add_i32 s54, s54, s48
	s_add_i32 s55, s54, -4
	s_max_i32 s55, s55, 0
	s_min_i32 s55, s55, 24
	s_add_i32 s73, s54, -3
	s_max_i32 s73, s73, 0
	s_min_i32 s73, s73, 24
	s_sub_i32 s73, s73, s55
	s_lshr_b32 s54, s57, 2
	s_mul_i32 s53, s73, s54
	s_ashr_i32 s54, s70, 6
	s_lshl_b32 s54, s54, 8
	s_lshl_b32 s55, s55, 3
	s_add_i32 s54, s54, s55
	s_add_i32 s54, s54, s57
	s_lshl_b32 s54, s54, 15
	s_lshl_b32 s55, s72, 11
	s_add_i32 s28, s54, s55
	s_lshl_b32 s54, s57, 10
	s_add_i32 s59, s54, 0x21000
	s_mov_b32 s75, 0x200000
	s_and_b32 s54, s57, 1
	s_lshl_b32 s54, s54, 1
	v_xor_b32_e32 v218, s54, v164
	v_lshlrev_b32_e32 v218, 4, v218
	v_add_u32_e32 v218, s28, v218
	ds_read_b64 v[220:221], v241 offset:192
	s_waitcnt lgkmcnt(0)
	v_add_co_u32_e32 v220, vcc, 0x21f00000, v220
	s_nop 1
	v_addc_co_u32_e32 v221, vcc, 0, v221, vcc
	v_add_co_u32_e32 v220, vcc, v220, v218
	s_nop 1
	v_addc_co_u32_e32 v221, vcc, 0, v221, vcc
	s_and_b32 s55, s57, 3
	s_lshl_b32 s55, s55, 1
	s_add_i32 s55, s55, -1
	s_max_i32 s55, s55, 0
	s_min_i32 s55, s55, 4
	v_lshrrev_b32_e32 v219, 2, v166
	v_add_u32_e32 v219, s55, v219
	v_and_b32_e32 v224, 3, v166
	v_lshl_or_b32 v224, v224, 2, v165
	v_and_b32_e32 v225, 1, v219
	v_lshlrev_b32_e32 v225, 1, v225
	v_xor_b32_e32 v224, v224, v225
	v_lshlrev_b32_e32 v224, 4, v224
	v_lshl_add_u32 v219, v219, 10, v224
	v_add_u32_e32 v219, 0x21000, v219
	s_barrier
	s_add_i32 m0, s59, 0
	s_nop 0
	global_load_lds_dwordx4 v[220:221], off
	s_add_i32 m0, s59, 7168
	s_nop 0
	global_load_lds_dwordx4 v[220:221], off offset:1024
	s_cmp_eq_u32 s53, 0
	s_cbranch_scc0 .Lring_k_B
	s_waitcnt vmcnt(1)
	s_barrier
	s_add_i32 m0, s59, 16384
	v_add_co_u32_e32 v222, vcc, s6, v220
	s_nop 1
	v_addc_co_u32_e32 v223, vcc, 0, v221, vcc
	global_load_lds_dwordx4 v[222:223], off
	ds_read_b128 v[2:5], v219 offset:0
	ds_read_b128 v[6:9], v219 offset:256
	ds_read_b128 v[10:13], v219 offset:512
	ds_read_b128 v[14:17], v219 offset:768
	s_waitcnt lgkmcnt(3)
	v_mfma_f32_16x16x32_bf16 v[126:129], v[2:5], v[138:141], 0
	s_waitcnt lgkmcnt(2)
	v_mfma_f32_16x16x32_bf16 v[122:125], v[6:9], v[138:141], 0
	s_waitcnt lgkmcnt(1)
	v_mfma_f32_16x16x32_bf16 v[126:129], v[10:13], v[134:137], v[126:129]
	s_waitcnt lgkmcnt(0)
	v_mfma_f32_16x16x32_bf16 v[122:125], v[14:17], v[134:137], v[122:125]
	s_waitcnt vmcnt(1)
	s_barrier
	s_add_i32 m0, s59, -1024
	v_add_co_u32_e32 v222, vcc, s6, v220
	s_nop 1
	v_addc_co_u32_e32 v223, vcc, 0, v221, vcc
	global_load_lds_dwordx4 v[222:223], off offset:1024
	ds_read_b128 v[18:21], v219 offset:8192
	ds_read_b128 v[22:25], v219 offset:8448
	ds_read_b128 v[26:29], v219 offset:8704
	ds_read_b128 v[30:33], v219 offset:8960
	s_waitcnt lgkmcnt(3)
	v_mfma_f32_16x16x32_bf16 v[126:129], v[18:21], v[130:133], v[126:129]
	s_waitcnt lgkmcnt(2)
	v_mfma_f32_16x16x32_bf16 v[122:125], v[22:25], v[130:133], v[122:125]
	s_waitcnt lgkmcnt(1)
	v_mfma_f32_16x16x32_bf16 v[126:129], v[26:29], v[62:65], v[126:129]
	s_waitcnt lgkmcnt(0)
	v_mfma_f32_16x16x32_bf16 v[122:125], v[30:33], v[62:65], v[122:125]
	s_waitcnt vmcnt(1)
	s_barrier
	s_add_i32 m0, s59, 8192
	v_add_co_u32_e32 v222, vcc, s7, v220
	s_nop 1
	v_addc_co_u32_e32 v223, vcc, 0, v221, vcc
	global_load_lds_dwordx4 v[222:223], off
	ds_read_b128 v[2:5], v219 offset:16384
	ds_read_b128 v[6:9], v219 offset:16640
	ds_read_b128 v[10:13], v219 offset:16896
	ds_read_b128 v[14:17], v219 offset:17152
	s_waitcnt lgkmcnt(3)
	v_mfma_f32_16x16x32_bf16 v[118:121], v[2:5], v[138:141], 0
	s_waitcnt lgkmcnt(2)
	v_mfma_f32_16x16x32_bf16 v[114:117], v[6:9], v[138:141], 0
	s_waitcnt lgkmcnt(1)
	v_mfma_f32_16x16x32_bf16 v[118:121], v[10:13], v[134:137], v[118:121]
	s_waitcnt lgkmcnt(0)
	v_mfma_f32_16x16x32_bf16 v[114:117], v[14:17], v[134:137], v[114:117]
	s_waitcnt vmcnt(1)
	s_barrier
	s_add_i32 m0, s59, 15360
	v_add_co_u32_e32 v222, vcc, s7, v220
	s_nop 1
	v_addc_co_u32_e32 v223, vcc, 0, v221, vcc
	global_load_lds_dwordx4 v[222:223], off offset:1024
	ds_read_b128 v[18:21], v219 offset:0
	ds_read_b128 v[22:25], v219 offset:256
	ds_read_b128 v[26:29], v219 offset:512
	ds_read_b128 v[30:33], v219 offset:768
	s_waitcnt lgkmcnt(3)
	v_mfma_f32_16x16x32_bf16 v[118:121], v[18:21], v[130:133], v[118:121]
	s_waitcnt lgkmcnt(2)
	v_mfma_f32_16x16x32_bf16 v[114:117], v[22:25], v[130:133], v[114:117]
	s_waitcnt lgkmcnt(1)
	v_mfma_f32_16x16x32_bf16 v[118:121], v[26:29], v[62:65], v[118:121]
	s_waitcnt lgkmcnt(0)
	v_mfma_f32_16x16x32_bf16 v[114:117], v[30:33], v[62:65], v[114:117]
	s_waitcnt vmcnt(1)
	s_barrier
	s_add_i32 m0, s59, 0
	v_add_co_u32_e32 v222, vcc, s2, v220
	s_nop 1
	v_addc_co_u32_e32 v223, vcc, 0, v221, vcc
	global_load_lds_dwordx4 v[222:223], off
	ds_read_b128 v[2:5], v219 offset:8192
	ds_read_b128 v[6:9], v219 offset:8448
	ds_read_b128 v[10:13], v219 offset:8704
	ds_read_b128 v[14:17], v219 offset:8960
	s_waitcnt lgkmcnt(3)
	v_mfma_f32_16x16x32_bf16 v[110:113], v[2:5], v[138:141], 0
	s_waitcnt lgkmcnt(2)
	v_mfma_f32_16x16x32_bf16 v[106:109], v[6:9], v[138:141], 0
	s_waitcnt lgkmcnt(1)
	v_mfma_f32_16x16x32_bf16 v[110:113], v[10:13], v[134:137], v[110:113]
	s_waitcnt lgkmcnt(0)
	v_mfma_f32_16x16x32_bf16 v[106:109], v[14:17], v[134:137], v[106:109]
	s_waitcnt vmcnt(1)
	s_barrier
; #define ATT_KLOAD(buf, p) do { const bf16_t* kp_ = kloc + (size_t)((p) * 8 * NH) * 1024; \
;         _Pragma("unroll") for (int f = 0; f < 2; ++f) _Pragma("unroll") for (int ks = 0; ks < 4; ++ks) ka[buf][f * 4 + ks] = *(const bf16x8*)(kp_ + f * 128 + ks * 256); } while (0)
; template <bool LOCAL>
; __device__ __forceinline__ void attn_unit(const bf16_t* Q, const bf16_t* KT, const bf16_t* VT, bf16_t* O, LAS unsigned char* lds, int b, int h, int r, int w, int tq, int lane) {
;     ...
;     if (LOCAL) {
;         const bf16_t* kloc = KT + ((size_t)(((rgl >> 3) + (q >> 2)) * NH + h)) * 1024 + (q & 3) * 32 + g * 8;
;         bf16x8 ka[2][8];
;     ...
;         ATT_KLOAD(0, 0);
; #pragma unroll
;         for (int p = 0; p < 8; ++p) {
;             __builtin_amdgcn_s_barrier();
;             if (p + 1 < 8) ATT_KLOAD((p + 1) & 1, p + 1);
;             __builtin_amdgcn_sched_barrier(0);
; #pragma unroll
;             for (int f = 0; f < 2; ++f) { f32x4 a = {0.f, 0.f, 0.f, 0.f};
; #pragma unroll
;                 for (int ks = 0; ks < 4; ++ks) a = __builtin_amdgcn_mfma_f32_16x16x32_bf16(ka[p & 1][f * 4 + ks], bq[ks], a, 0, 0, 0);
;                 s[2 * p + f] = a; }
;             __builtin_amdgcn_sched_barrier(0);
;         }
	s_add_i32 m0, s59, 7168
	v_add_co_u32_e32 v222, vcc, s2, v220
	s_nop 1
	v_addc_co_u32_e32 v223, vcc, 0, v221, vcc
	global_load_lds_dwordx4 v[222:223], off offset:1024
	ds_read_b128 v[18:21], v219 offset:16384
	ds_read_b128 v[22:25], v219 offset:16640
	ds_read_b128 v[26:29], v219 offset:16896
	ds_read_b128 v[30:33], v219 offset:17152
	s_waitcnt lgkmcnt(3)
	v_mfma_f32_16x16x32_bf16 v[110:113], v[18:21], v[130:133], v[110:113]
	s_waitcnt lgkmcnt(2)
	v_mfma_f32_16x16x32_bf16 v[106:109], v[22:25], v[130:133], v[106:109]
	s_waitcnt lgkmcnt(1)
	v_mfma_f32_16x16x32_bf16 v[110:113], v[26:29], v[62:65], v[110:113]
	s_waitcnt lgkmcnt(0)
	v_mfma_f32_16x16x32_bf16 v[106:109], v[30:33], v[62:65], v[106:109]
	s_waitcnt vmcnt(1)
	s_barrier
	s_add_i32 m0, s59, 16384
	v_add_co_u32_e32 v222, vcc, s60, v220
	s_nop 1
	v_addc_co_u32_e32 v223, vcc, 0, v221, vcc
	global_load_lds_dwordx4 v[222:223], off
	ds_read_b128 v[2:5], v219 offset:0
	ds_read_b128 v[6:9], v219 offset:256
	ds_read_b128 v[10:13], v219 offset:512
	ds_read_b128 v[14:17], v219 offset:768
	s_waitcnt lgkmcnt(3)
	v_mfma_f32_16x16x32_bf16 v[102:105], v[2:5], v[138:141], 0
	s_waitcnt lgkmcnt(2)
	v_mfma_f32_16x16x32_bf16 v[98:101], v[6:9], v[138:141], 0
	s_waitcnt lgkmcnt(1)
	v_mfma_f32_16x16x32_bf16 v[102:105], v[10:13], v[134:137], v[102:105]
	s_waitcnt lgkmcnt(0)
	v_mfma_f32_16x16x32_bf16 v[98:101], v[14:17], v[134:137], v[98:101]
	s_waitcnt vmcnt(1)
	s_barrier
	s_add_i32 m0, s59, -1024
	v_add_co_u32_e32 v222, vcc, s60, v220
	s_nop 1
	v_addc_co_u32_e32 v223, vcc, 0, v221, vcc
	global_load_lds_dwordx4 v[222:223], off offset:1024
	ds_read_b128 v[18:21], v219 offset:8192
	ds_read_b128 v[22:25], v219 offset:8448
	ds_read_b128 v[26:29], v219 offset:8704
	ds_read_b128 v[30:33], v219 offset:8960
	s_waitcnt lgkmcnt(3)
	v_mfma_f32_16x16x32_bf16 v[102:105], v[18:21], v[130:133], v[102:105]
	s_waitcnt lgkmcnt(2)
	v_mfma_f32_16x16x32_bf16 v[98:101], v[22:25], v[130:133], v[98:101]
	s_waitcnt lgkmcnt(1)
	v_mfma_f32_16x16x32_bf16 v[102:105], v[26:29], v[62:65], v[102:105]
	s_waitcnt lgkmcnt(0)
	v_mfma_f32_16x16x32_bf16 v[98:101], v[30:33], v[62:65], v[98:101]
	s_waitcnt vmcnt(1)
	s_barrier
	s_add_i32 m0, s59, 8192
	v_add_co_u32_e32 v222, vcc, s61, v220
	s_nop 1
	v_addc_co_u32_e32 v223, vcc, 0, v221, vcc
	global_load_lds_dwordx4 v[222:223], off
	ds_read_b128 v[2:5], v219 offset:16384
	ds_read_b128 v[6:9], v219 offset:16640
	ds_read_b128 v[10:13], v219 offset:16896
	ds_read_b128 v[14:17], v219 offset:17152
	s_waitcnt lgkmcnt(3)
	v_mfma_f32_16x16x32_bf16 v[94:97], v[2:5], v[138:141], 0
	s_waitcnt lgkmcnt(2)
	v_mfma_f32_16x16x32_bf16 v[90:93], v[6:9], v[138:141], 0
	s_waitcnt lgkmcnt(1)
	v_mfma_f32_16x16x32_bf16 v[94:97], v[10:13], v[134:137], v[94:97]
	s_waitcnt lgkmcnt(0)
	v_mfma_f32_16x16x32_bf16 v[90:93], v[14:17], v[134:137], v[90:93]
	s_waitcnt vmcnt(1)
	s_barrier
	s_add_i32 m0, s59, 15360
	v_add_co_u32_e32 v222, vcc, s61, v220
	s_nop 1
	v_addc_co_u32_e32 v223, vcc, 0, v221, vcc
	global_load_lds_dwordx4 v[222:223], off offset:1024
	ds_read_b128 v[18:21], v219 offset:0
	ds_read_b128 v[22:25], v219 offset:256
	ds_read_b128 v[26:29], v219 offset:512
	ds_read_b128 v[30:33], v219 offset:768
	s_waitcnt lgkmcnt(3)
	v_mfma_f32_16x16x32_bf16 v[94:97], v[18:21], v[130:133], v[94:97]
	s_waitcnt lgkmcnt(2)
	v_mfma_f32_16x16x32_bf16 v[90:93], v[22:25], v[130:133], v[90:93]
	s_waitcnt lgkmcnt(1)
	v_mfma_f32_16x16x32_bf16 v[94:97], v[26:29], v[62:65], v[94:97]
	s_waitcnt lgkmcnt(0)
	v_mfma_f32_16x16x32_bf16 v[90:93], v[30:33], v[62:65], v[90:93]
	s_waitcnt vmcnt(1)
	s_barrier
	s_add_i32 m0, s59, 0
	v_add_co_u32_e32 v222, vcc, s17, v220
	s_nop 1
	v_addc_co_u32_e32 v223, vcc, 0, v221, vcc
	global_load_lds_dwordx4 v[222:223], off
	ds_read_b128 v[2:5], v219 offset:8192
	ds_read_b128 v[6:9], v219 offset:8448
	ds_read_b128 v[10:13], v219 offset:8704
	ds_read_b128 v[14:17], v219 offset:8960
	s_waitcnt lgkmcnt(3)
	v_mfma_f32_16x16x32_bf16 v[86:89], v[2:5], v[138:141], 0
	s_waitcnt lgkmcnt(2)
	v_mfma_f32_16x16x32_bf16 v[82:85], v[6:9], v[138:141], 0
	s_waitcnt lgkmcnt(1)
	v_mfma_f32_16x16x32_bf16 v[86:89], v[10:13], v[134:137], v[86:89]
	s_waitcnt lgkmcnt(0)
	v_mfma_f32_16x16x32_bf16 v[82:85], v[14:17], v[134:137], v[82:85]
	s_waitcnt vmcnt(1)
	s_barrier
	s_add_i32 m0, s59, 7168
	v_add_co_u32_e32 v222, vcc, s17, v220
	s_nop 1
	v_addc_co_u32_e32 v223, vcc, 0, v221, vcc
	global_load_lds_dwordx4 v[222:223], off offset:1024
	ds_read_b128 v[18:21], v219 offset:16384
	ds_read_b128 v[22:25], v219 offset:16640
	ds_read_b128 v[26:29], v219 offset:16896
	ds_read_b128 v[30:33], v219 offset:17152
	s_waitcnt lgkmcnt(3)
	v_mfma_f32_16x16x32_bf16 v[86:89], v[18:21], v[130:133], v[86:89]
	s_waitcnt lgkmcnt(2)
	v_mfma_f32_16x16x32_bf16 v[82:85], v[22:25], v[130:133], v[82:85]
	s_waitcnt lgkmcnt(1)
	v_mfma_f32_16x16x32_bf16 v[86:89], v[26:29], v[62:65], v[86:89]
	s_waitcnt lgkmcnt(0)
	v_mfma_f32_16x16x32_bf16 v[82:85], v[30:33], v[62:65], v[82:85]
	s_waitcnt vmcnt(1)
	s_barrier
	s_add_i32 m0, s59, 16384
	v_add_co_u32_e32 v222, vcc, s62, v220
	s_nop 1
	v_addc_co_u32_e32 v223, vcc, 0, v221, vcc
	global_load_lds_dwordx4 v[222:223], off
	ds_read_b128 v[2:5], v219 offset:0
	ds_read_b128 v[6:9], v219 offset:256
	ds_read_b128 v[10:13], v219 offset:512
	ds_read_b128 v[14:17], v219 offset:768
	s_waitcnt lgkmcnt(3)
	v_mfma_f32_16x16x32_bf16 v[78:81], v[2:5], v[138:141], 0
	s_waitcnt lgkmcnt(2)
	v_mfma_f32_16x16x32_bf16 v[74:77], v[6:9], v[138:141], 0
	s_waitcnt lgkmcnt(1)
	v_mfma_f32_16x16x32_bf16 v[78:81], v[10:13], v[134:137], v[78:81]
	s_waitcnt lgkmcnt(0)
	v_mfma_f32_16x16x32_bf16 v[74:77], v[14:17], v[134:137], v[74:77]
	s_waitcnt vmcnt(1)
	s_barrier
	s_add_i32 m0, s59, -1024
	v_add_co_u32_e32 v222, vcc, s62, v220
	s_nop 1
	v_addc_co_u32_e32 v223, vcc, 0, v221, vcc
	global_load_lds_dwordx4 v[222:223], off offset:1024
	ds_read_b128 v[18:21], v219 offset:8192
	ds_read_b128 v[22:25], v219 offset:8448
	ds_read_b128 v[26:29], v219 offset:8704
	ds_read_b128 v[30:33], v219 offset:8960
	s_waitcnt lgkmcnt(3)
	v_mfma_f32_16x16x32_bf16 v[78:81], v[18:21], v[130:133], v[78:81]
	s_waitcnt lgkmcnt(2)
	v_mfma_f32_16x16x32_bf16 v[74:77], v[22:25], v[130:133], v[74:77]
	s_waitcnt lgkmcnt(1)
	v_mfma_f32_16x16x32_bf16 v[78:81], v[26:29], v[62:65], v[78:81]
	s_waitcnt lgkmcnt(0)
	v_mfma_f32_16x16x32_bf16 v[74:77], v[30:33], v[62:65], v[74:77]
	s_waitcnt vmcnt(1)
	s_barrier
	s_cmp_eq_u32 s73, 0
	s_cbranch_scc1 .Lring_k_A_nd14
	s_add_i32 m0, s59, 8192
	v_add_co_u32_e32 v222, vcc, s75, v220
	s_nop 1
	v_addc_co_u32_e32 v223, vcc, 0, v221, vcc
	global_load_lds_dwordx4 v[222:223], off
; #define ATT_KLOAD(buf, p) do { const bf16_t* kp_ = kloc + (size_t)((p) * 8 * NH) * 1024; \
;         _Pragma("unroll") for (int f = 0; f < 2; ++f) _Pragma("unroll") for (int ks = 0; ks < 4; ++ks) ka[buf][f * 4 + ks] = *(const bf16x8*)(kp_ + f * 128 + ks * 256); } while (0)
; template <bool LOCAL>
; __device__ __forceinline__ void attn_unit(const bf16_t* Q, const bf16_t* KT, const bf16_t* VT, bf16_t* O, LAS unsigned char* lds, int b, int h, int r, int w, int tq, int lane) {
;     ...
;     if (LOCAL) {
;         const bf16_t* kloc = KT + ((size_t)(((rgl >> 3) + (q >> 2)) * NH + h)) * 1024 + (q & 3) * 32 + g * 8;
;         bf16x8 ka[2][8];
;     ...
;         ATT_KLOAD(0, 0);
; #pragma unroll
;         for (int p = 0; p < 8; ++p) {
;             __builtin_amdgcn_s_barrier();
;             if (p + 1 < 8) ATT_KLOAD((p + 1) & 1, p + 1);
;             __builtin_amdgcn_sched_barrier(0);
; #pragma unroll
;             for (int f = 0; f < 2; ++f) { f32x4 a = {0.f, 0.f, 0.f, 0.f};
; #pragma unroll
;                 for (int ks = 0; ks < 4; ++ks) a = __builtin_amdgcn_mfma_f32_16x16x32_bf16(ka[p & 1][f * 4 + ks], bq[ks], a, 0, 0, 0);
;                 s[2 * p + f] = a; }
;             __builtin_amdgcn_sched_barrier(0);
;         }
.Lring_k_A_nd14:
	ds_read_b128 v[2:5], v219 offset:16384
	ds_read_b128 v[6:9], v219 offset:16640
	ds_read_b128 v[10:13], v219 offset:16896
	ds_read_b128 v[14:17], v219 offset:17152
	s_waitcnt lgkmcnt(3)
	v_mfma_f32_16x16x32_bf16 v[70:73], v[2:5], v[138:141], 0
	s_waitcnt lgkmcnt(2)
	v_mfma_f32_16x16x32_bf16 v[66:69], v[6:9], v[138:141], 0
	s_waitcnt lgkmcnt(1)
	v_mfma_f32_16x16x32_bf16 v[70:73], v[10:13], v[134:137], v[70:73]
	s_waitcnt lgkmcnt(0)
	v_mfma_f32_16x16x32_bf16 v[66:69], v[14:17], v[134:137], v[66:69]
	s_cmp_eq_u32 s73, 0
	s_cbranch_scc1 .Lring_k_A_w15
	s_waitcnt vmcnt(1)
	s_branch .Lring_k_A_b15

; #define ATT_KLOAD(buf, p) do { const bf16_t* kp_ = kloc + (size_t)((p) * 8 * NH) * 1024; \
;         _Pragma("unroll") for (int f = 0; f < 2; ++f) _Pragma("unroll") for (int ks = 0; ks < 4; ++ks) ka[buf][f * 4 + ks] = *(const bf16x8*)(kp_ + f * 128 + ks * 256); } while (0)
; template <bool LOCAL>
; __device__ __forceinline__ void attn_unit(const bf16_t* Q, const bf16_t* KT, const bf16_t* VT, bf16_t* O, LAS unsigned char* lds, int b, int h, int r, int w, int tq, int lane) {
;     ...
;     if (LOCAL) {
;         const bf16_t* kloc = KT + ((size_t)(((rgl >> 3) + (q >> 2)) * NH + h)) * 1024 + (q & 3) * 32 + g * 8;
;         bf16x8 ka[2][8];
;     ...
;         ATT_KLOAD(0, 0);
; #pragma unroll
;         for (int p = 0; p < 8; ++p) {
;             __builtin_amdgcn_s_barrier();
;             if (p + 1 < 8) ATT_KLOAD((p + 1) & 1, p + 1);
;             __builtin_amdgcn_sched_barrier(0);
; #pragma unroll
;             for (int f = 0; f < 2; ++f) { f32x4 a = {0.f, 0.f, 0.f, 0.f};
; #pragma unroll
;                 for (int ks = 0; ks < 4; ++ks) a = __builtin_amdgcn_mfma_f32_16x16x32_bf16(ka[p & 1][f * 4 + ks], bq[ks], a, 0, 0, 0);
;                 s[2 * p + f] = a; }
;             __builtin_amdgcn_sched_barrier(0);
;         }
.Lring_k_A_nd15:
	ds_read_b128 v[18:21], v219 offset:0
	ds_read_b128 v[22:25], v219 offset:256
	ds_read_b128 v[26:29], v219 offset:512
	ds_read_b128 v[30:33], v219 offset:768
	s_waitcnt lgkmcnt(3)
	v_mfma_f32_16x16x32_bf16 v[70:73], v[18:21], v[130:133], v[70:73]
	s_waitcnt lgkmcnt(2)
	v_mfma_f32_16x16x32_bf16 v[66:69], v[22:25], v[130:133], v[66:69]
	s_waitcnt lgkmcnt(1)
	v_mfma_f32_16x16x32_bf16 v[70:73], v[26:29], v[62:65], v[70:73]
	s_waitcnt lgkmcnt(0)
	v_mfma_f32_16x16x32_bf16 v[66:69], v[30:33], v[62:65], v[66:69]
	s_cmp_eq_u32 s73, 0
	s_cbranch_scc1 .Lring_k_A_end
	s_waitcnt vmcnt(1)
	s_barrier
	s_waitcnt vmcnt(0)
	s_barrier

; #define ATT_KLOAD(buf, p) do { const bf16_t* kp_ = kloc + (size_t)((p) * 8 * NH) * 1024; \
;         _Pragma("unroll") for (int f = 0; f < 2; ++f) _Pragma("unroll") for (int ks = 0; ks < 4; ++ks) ka[buf][f * 4 + ks] = *(const bf16x8*)(kp_ + f * 128 + ks * 256); } while (0)
; template <bool LOCAL>
; __device__ __forceinline__ void attn_unit(const bf16_t* Q, const bf16_t* KT, const bf16_t* VT, bf16_t* O, LAS unsigned char* lds, int b, int h, int r, int w, int tq, int lane) {
;     ...
;     if (LOCAL) {
;         const bf16_t* kloc = KT + ((size_t)(((rgl >> 3) + (q >> 2)) * NH + h)) * 1024 + (q & 3) * 32 + g * 8;
;         bf16x8 ka[2][8];
;     ...
;         ATT_KLOAD(0, 0);
; #pragma unroll
;         for (int p = 0; p < 8; ++p) {
;             __builtin_amdgcn_s_barrier();
;             if (p + 1 < 8) ATT_KLOAD((p + 1) & 1, p + 1);
;             __builtin_amdgcn_sched_barrier(0);
; #pragma unroll
;             for (int f = 0; f < 2; ++f) { f32x4 a = {0.f, 0.f, 0.f, 0.f};
; #pragma unroll
;                 for (int ks = 0; ks < 4; ++ks) a = __builtin_amdgcn_mfma_f32_16x16x32_bf16(ka[p & 1][f * 4 + ks], bq[ks], a, 0, 0, 0);
;                 s[2 * p + f] = a; }
;             __builtin_amdgcn_sched_barrier(0);
;         }
.Lring_k_B:
	s_waitcnt vmcnt(1)
	s_barrier
	s_add_i32 m0, s59, 16384
	v_add_co_u32_e32 v222, vcc, s6, v220
	s_nop 1
	v_addc_co_u32_e32 v223, vcc, 0, v221, vcc
	global_load_lds_dwordx4 v[222:223], off
	s_waitcnt vmcnt(1)
	s_barrier
	s_add_i32 m0, s59, -1024
	v_add_co_u32_e32 v222, vcc, s6, v220
	s_nop 1
	v_addc_co_u32_e32 v223, vcc, 0, v221, vcc
	global_load_lds_dwordx4 v[222:223], off offset:1024
	s_waitcnt vmcnt(1)
	s_barrier
	s_add_i32 m0, s59, 8192
	v_add_co_u32_e32 v222, vcc, s7, v220
	s_nop 1
	v_addc_co_u32_e32 v223, vcc, 0, v221, vcc
	global_load_lds_dwordx4 v[222:223], off
	ds_read_b128 v[2:5], v219 offset:16384
	ds_read_b128 v[6:9], v219 offset:16640
	ds_read_b128 v[10:13], v219 offset:16896
	ds_read_b128 v[14:17], v219 offset:17152
	s_waitcnt lgkmcnt(3)
	v_mfma_f32_16x16x32_bf16 v[126:129], v[2:5], v[138:141], 0
	s_waitcnt lgkmcnt(2)
	v_mfma_f32_16x16x32_bf16 v[122:125], v[6:9], v[138:141], 0
	s_waitcnt lgkmcnt(1)
	v_mfma_f32_16x16x32_bf16 v[126:129], v[10:13], v[134:137], v[126:129]
	s_waitcnt lgkmcnt(0)
	v_mfma_f32_16x16x32_bf16 v[122:125], v[14:17], v[134:137], v[122:125]
	s_waitcnt vmcnt(1)
	s_barrier
	s_add_i32 m0, s59, 15360
	v_add_co_u32_e32 v222, vcc, s7, v220
	s_nop 1
	v_addc_co_u32_e32 v223, vcc, 0, v221, vcc
	global_load_lds_dwordx4 v[222:223], off offset:1024
	ds_read_b128 v[18:21], v219 offset:0
	ds_read_b128 v[22:25], v219 offset:256
	ds_read_b128 v[26:29], v219 offset:512
	ds_read_b128 v[30:33], v219 offset:768
	s_waitcnt lgkmcnt(3)
	v_mfma_f32_16x16x32_bf16 v[126:129], v[18:21], v[130:133], v[126:129]
	s_waitcnt lgkmcnt(2)
	v_mfma_f32_16x16x32_bf16 v[122:125], v[22:25], v[130:133], v[122:125]
	s_waitcnt lgkmcnt(1)
	v_mfma_f32_16x16x32_bf16 v[126:129], v[26:29], v[62:65], v[126:129]
	s_waitcnt lgkmcnt(0)
	v_mfma_f32_16x16x32_bf16 v[122:125], v[30:33], v[62:65], v[122:125]
	s_waitcnt vmcnt(1)
	s_barrier
	s_add_i32 m0, s59, 0
	v_add_co_u32_e32 v222, vcc, s2, v220
	s_nop 1
	v_addc_co_u32_e32 v223, vcc, 0, v221, vcc
	global_load_lds_dwordx4 v[222:223], off
	ds_read_b128 v[2:5], v219 offset:8192
	ds_read_b128 v[6:9], v219 offset:8448
	ds_read_b128 v[10:13], v219 offset:8704
	ds_read_b128 v[14:17], v219 offset:8960
	s_waitcnt lgkmcnt(3)
	v_mfma_f32_16x16x32_bf16 v[118:121], v[2:5], v[138:141], 0
	s_waitcnt lgkmcnt(2)
	v_mfma_f32_16x16x32_bf16 v[114:117], v[6:9], v[138:141], 0
	s_waitcnt lgkmcnt(1)
	v_mfma_f32_16x16x32_bf16 v[118:121], v[10:13], v[134:137], v[118:121]
	s_waitcnt lgkmcnt(0)
	v_mfma_f32_16x16x32_bf16 v[114:117], v[14:17], v[134:137], v[114:117]
	s_waitcnt vmcnt(1)
	s_barrier
	s_add_i32 m0, s59, 7168
	v_add_co_u32_e32 v222, vcc, s2, v220
	s_nop 1
	v_addc_co_u32_e32 v223, vcc, 0, v221, vcc
	global_load_lds_dwordx4 v[222:223], off offset:1024
	ds_read_b128 v[18:21], v219 offset:16384
	ds_read_b128 v[22:25], v219 offset:16640
	ds_read_b128 v[26:29], v219 offset:16896
	ds_read_b128 v[30:33], v219 offset:17152
	s_waitcnt lgkmcnt(3)
	v_mfma_f32_16x16x32_bf16 v[118:121], v[18:21], v[130:133], v[118:121]
	s_waitcnt lgkmcnt(2)
	v_mfma_f32_16x16x32_bf16 v[114:117], v[22:25], v[130:133], v[114:117]
	s_waitcnt lgkmcnt(1)
	v_mfma_f32_16x16x32_bf16 v[118:121], v[26:29], v[62:65], v[118:121]
	s_waitcnt lgkmcnt(0)
	v_mfma_f32_16x16x32_bf16 v[114:117], v[30:33], v[62:65], v[114:117]
	s_waitcnt vmcnt(1)
	s_barrier
	s_add_i32 m0, s59, 16384
	v_add_co_u32_e32 v222, vcc, s60, v220
	s_nop 1
	v_addc_co_u32_e32 v223, vcc, 0, v221, vcc
	global_load_lds_dwordx4 v[222:223], off
	ds_read_b128 v[2:5], v219 offset:0
	ds_read_b128 v[6:9], v219 offset:256
	ds_read_b128 v[10:13], v219 offset:512
	ds_read_b128 v[14:17], v219 offset:768
	s_waitcnt lgkmcnt(3)
	v_mfma_f32_16x16x32_bf16 v[110:113], v[2:5], v[138:141], 0
	s_waitcnt lgkmcnt(2)
	v_mfma_f32_16x16x32_bf16 v[106:109], v[6:9], v[138:141], 0
	s_waitcnt lgkmcnt(1)
	v_mfma_f32_16x16x32_bf16 v[110:113], v[10:13], v[134:137], v[110:113]
	s_waitcnt lgkmcnt(0)
	v_mfma_f32_16x16x32_bf16 v[106:109], v[14:17], v[134:137], v[106:109]
	s_waitcnt vmcnt(1)
	s_barrier
	s_add_i32 m0, s59, -1024
	v_add_co_u32_e32 v222, vcc, s60, v220
	s_nop 1
	v_addc_co_u32_e32 v223, vcc, 0, v221, vcc
	global_load_lds_dwordx4 v[222:223], off offset:1024
	ds_read_b128 v[18:21], v219 offset:8192
	ds_read_b128 v[22:25], v219 offset:8448
	ds_read_b128 v[26:29], v219 offset:8704
	ds_read_b128 v[30:33], v219 offset:8960
	s_waitcnt lgkmcnt(3)
	v_mfma_f32_16x16x32_bf16 v[110:113], v[18:21], v[130:133], v[110:113]
	s_waitcnt lgkmcnt(2)
	v_mfma_f32_16x16x32_bf16 v[106:109], v[22:25], v[130:133], v[106:109]
	s_waitcnt lgkmcnt(1)
	v_mfma_f32_16x16x32_bf16 v[110:113], v[26:29], v[62:65], v[110:113]
	s_waitcnt lgkmcnt(0)
	v_mfma_f32_16x16x32_bf16 v[106:109], v[30:33], v[62:65], v[106:109]
	s_waitcnt vmcnt(1)
	s_barrier
; #define ATT_KLOAD(buf, p) do { const bf16_t* kp_ = kloc + (size_t)((p) * 8 * NH) * 1024; \
;         _Pragma("unroll") for (int f = 0; f < 2; ++f) _Pragma("unroll") for (int ks = 0; ks < 4; ++ks) ka[buf][f * 4 + ks] = *(const bf16x8*)(kp_ + f * 128 + ks * 256); } while (0)
; template <bool LOCAL>
; __device__ __forceinline__ void attn_unit(const bf16_t* Q, const bf16_t* KT, const bf16_t* VT, bf16_t* O, LAS unsigned char* lds, int b, int h, int r, int w, int tq, int lane) {
;     ...
;     if (LOCAL) {
;         const bf16_t* kloc = KT + ((size_t)(((rgl >> 3) + (q >> 2)) * NH + h)) * 1024 + (q & 3) * 32 + g * 8;
;         bf16x8 ka[2][8];
;     ...
;         ATT_KLOAD(0, 0);
; #pragma unroll
;         for (int p = 0; p < 8; ++p) {
;             __builtin_amdgcn_s_barrier();
;             if (p + 1 < 8) ATT_KLOAD((p + 1) & 1, p + 1);
;             __builtin_amdgcn_sched_barrier(0);
; #pragma unroll
;             for (int f = 0; f < 2; ++f) { f32x4 a = {0.f, 0.f, 0.f, 0.f};
; #pragma unroll
;                 for (int ks = 0; ks < 4; ++ks) a = __builtin_amdgcn_mfma_f32_16x16x32_bf16(ka[p & 1][f * 4 + ks], bq[ks], a, 0, 0, 0);
;                 s[2 * p + f] = a; }
;             __builtin_amdgcn_sched_barrier(0);
;         }
	s_add_i32 m0, s59, 8192
	v_add_co_u32_e32 v222, vcc, s61, v220
	s_nop 1
	v_addc_co_u32_e32 v223, vcc, 0, v221, vcc
	global_load_lds_dwordx4 v[222:223], off
	ds_read_b128 v[2:5], v219 offset:16384
	ds_read_b128 v[6:9], v219 offset:16640
	ds_read_b128 v[10:13], v219 offset:16896
	ds_read_b128 v[14:17], v219 offset:17152
	s_waitcnt lgkmcnt(3)
	v_mfma_f32_16x16x32_bf16 v[102:105], v[2:5], v[138:141], 0
	s_waitcnt lgkmcnt(2)
	v_mfma_f32_16x16x32_bf16 v[98:101], v[6:9], v[138:141], 0
	s_waitcnt lgkmcnt(1)
	v_mfma_f32_16x16x32_bf16 v[102:105], v[10:13], v[134:137], v[102:105]
	s_waitcnt lgkmcnt(0)
	v_mfma_f32_16x16x32_bf16 v[98:101], v[14:17], v[134:137], v[98:101]
	s_waitcnt vmcnt(1)
	s_barrier
	s_add_i32 m0, s59, 15360
	v_add_co_u32_e32 v222, vcc, s61, v220
	s_nop 1
	v_addc_co_u32_e32 v223, vcc, 0, v221, vcc
	global_load_lds_dwordx4 v[222:223], off offset:1024
	ds_read_b128 v[18:21], v219 offset:0
	ds_read_b128 v[22:25], v219 offset:256
	ds_read_b128 v[26:29], v219 offset:512
	ds_read_b128 v[30:33], v219 offset:768
	s_waitcnt lgkmcnt(3)
	v_mfma_f32_16x16x32_bf16 v[102:105], v[18:21], v[130:133], v[102:105]
	s_waitcnt lgkmcnt(2)
	v_mfma_f32_16x16x32_bf16 v[98:101], v[22:25], v[130:133], v[98:101]
	s_waitcnt lgkmcnt(1)
	v_mfma_f32_16x16x32_bf16 v[102:105], v[26:29], v[62:65], v[102:105]
	s_waitcnt lgkmcnt(0)
	v_mfma_f32_16x16x32_bf16 v[98:101], v[30:33], v[62:65], v[98:101]
	s_waitcnt vmcnt(1)
	s_barrier
	s_add_i32 m0, s59, 0
	v_add_co_u32_e32 v222, vcc, s17, v220
	s_nop 1
	v_addc_co_u32_e32 v223, vcc, 0, v221, vcc
	global_load_lds_dwordx4 v[222:223], off
	ds_read_b128 v[2:5], v219 offset:8192
	ds_read_b128 v[6:9], v219 offset:8448
	ds_read_b128 v[10:13], v219 offset:8704
	ds_read_b128 v[14:17], v219 offset:8960
	s_waitcnt lgkmcnt(3)
	v_mfma_f32_16x16x32_bf16 v[94:97], v[2:5], v[138:141], 0
	s_waitcnt lgkmcnt(2)
	v_mfma_f32_16x16x32_bf16 v[90:93], v[6:9], v[138:141], 0
	s_waitcnt lgkmcnt(1)
	v_mfma_f32_16x16x32_bf16 v[94:97], v[10:13], v[134:137], v[94:97]
	s_waitcnt lgkmcnt(0)
	v_mfma_f32_16x16x32_bf16 v[90:93], v[14:17], v[134:137], v[90:93]
	s_waitcnt vmcnt(1)
	s_barrier
	s_add_i32 m0, s59, 7168
	v_add_co_u32_e32 v222, vcc, s17, v220
	s_nop 1
	v_addc_co_u32_e32 v223, vcc, 0, v221, vcc
	global_load_lds_dwordx4 v[222:223], off offset:1024
	ds_read_b128 v[18:21], v219 offset:16384
	ds_read_b128 v[22:25], v219 offset:16640
	ds_read_b128 v[26:29], v219 offset:16896
	ds_read_b128 v[30:33], v219 offset:17152
	s_waitcnt lgkmcnt(3)
	v_mfma_f32_16x16x32_bf16 v[94:97], v[18:21], v[130:133], v[94:97]
	s_waitcnt lgkmcnt(2)
	v_mfma_f32_16x16x32_bf16 v[90:93], v[22:25], v[130:133], v[90:93]
	s_waitcnt lgkmcnt(1)
	v_mfma_f32_16x16x32_bf16 v[94:97], v[26:29], v[62:65], v[94:97]
	s_waitcnt lgkmcnt(0)
	v_mfma_f32_16x16x32_bf16 v[90:93], v[30:33], v[62:65], v[90:93]
	s_waitcnt vmcnt(1)
	s_barrier
	s_add_i32 m0, s59, 16384
	v_add_co_u32_e32 v222, vcc, s62, v220
	s_nop 1
	v_addc_co_u32_e32 v223, vcc, 0, v221, vcc
	global_load_lds_dwordx4 v[222:223], off
	ds_read_b128 v[2:5], v219 offset:0
	ds_read_b128 v[6:9], v219 offset:256
	ds_read_b128 v[10:13], v219 offset:512
	ds_read_b128 v[14:17], v219 offset:768
	s_waitcnt lgkmcnt(3)
	v_mfma_f32_16x16x32_bf16 v[86:89], v[2:5], v[138:141], 0
	s_waitcnt lgkmcnt(2)
	v_mfma_f32_16x16x32_bf16 v[82:85], v[6:9], v[138:141], 0
	s_waitcnt lgkmcnt(1)
	v_mfma_f32_16x16x32_bf16 v[86:89], v[10:13], v[134:137], v[86:89]
	s_waitcnt lgkmcnt(0)
	v_mfma_f32_16x16x32_bf16 v[82:85], v[14:17], v[134:137], v[82:85]
	s_waitcnt vmcnt(1)
	s_barrier
	s_add_i32 m0, s59, -1024
	v_add_co_u32_e32 v222, vcc, s62, v220
	s_nop 1
	v_addc_co_u32_e32 v223, vcc, 0, v221, vcc
	global_load_lds_dwordx4 v[222:223], off offset:1024
	ds_read_b128 v[18:21], v219 offset:8192
	ds_read_b128 v[22:25], v219 offset:8448
	ds_read_b128 v[26:29], v219 offset:8704
	ds_read_b128 v[30:33], v219 offset:8960
	s_waitcnt lgkmcnt(3)
	v_mfma_f32_16x16x32_bf16 v[86:89], v[18:21], v[130:133], v[86:89]
	s_waitcnt lgkmcnt(2)
	v_mfma_f32_16x16x32_bf16 v[82:85], v[22:25], v[130:133], v[82:85]
	s_waitcnt lgkmcnt(1)
	v_mfma_f32_16x16x32_bf16 v[86:89], v[26:29], v[62:65], v[86:89]
	s_waitcnt lgkmcnt(0)
	v_mfma_f32_16x16x32_bf16 v[82:85], v[30:33], v[62:65], v[82:85]
	s_waitcnt vmcnt(1)
	s_barrier
	s_cmp_eq_u32 s73, 0
	s_cbranch_scc1 .Lring_k_B_nd14
	s_add_i32 m0, s59, 8192
	v_add_co_u32_e32 v222, vcc, s75, v220
	s_nop 1
	v_addc_co_u32_e32 v223, vcc, 0, v221, vcc
	global_load_lds_dwordx4 v[222:223], off
.Lring_k_B_nd14:
	ds_read_b128 v[2:5], v219 offset:16384
	ds_read_b128 v[6:9], v219 offset:16640
	ds_read_b128 v[10:13], v219 offset:16896
	ds_read_b128 v[14:17], v219 offset:17152
	s_waitcnt lgkmcnt(3)
	v_mfma_f32_16x16x32_bf16 v[78:81], v[2:5], v[138:141], 0
	s_waitcnt lgkmcnt(2)
	v_mfma_f32_16x16x32_bf16 v[74:77], v[6:9], v[138:141], 0
	s_waitcnt lgkmcnt(1)
	v_mfma_f32_16x16x32_bf16 v[78:81], v[10:13], v[134:137], v[78:81]
	s_waitcnt lgkmcnt(0)
	v_mfma_f32_16x16x32_bf16 v[74:77], v[14:17], v[134:137], v[74:77]
	s_cmp_eq_u32 s73, 0
	s_cbranch_scc1 .Lring_k_B_w15
	s_waitcnt vmcnt(1)
	s_branch .Lring_k_B_b15

; #define LAS __attribute__((address_space(3)))
; #define ATT_KLOAD(buf, p) do { const bf16_t* kp_ = kloc + (size_t)((p) * 8 * NH) * 1024; \
;         _Pragma("unroll") for (int f = 0; f < 2; ++f) _Pragma("unroll") for (int ks = 0; ks < 4; ++ks) ka[buf][f * 4 + ks] = *(const bf16x8*)(kp_ + f * 128 + ks * 256); } while (0)
; template <bool LOCAL>
; __device__ __forceinline__ void attn_unit(const bf16_t* Q, const bf16_t* KT, const bf16_t* VT, bf16_t* O, LAS unsigned char* lds, int b, int h, int r, int w, int tq, int lane) {
;     ...
;         for (int p = 0; p < 8; ++p) {
;             __builtin_amdgcn_s_barrier();
;             if (p + 1 < 8) ATT_KLOAD((p + 1) & 1, p + 1);
;             __builtin_amdgcn_sched_barrier(0);
; #pragma unroll
;             for (int f = 0; f < 2; ++f) { f32x4 a = {0.f, 0.f, 0.f, 0.f};
; #pragma unroll
;                 for (int ks = 0; ks < 4; ++ks) a = __builtin_amdgcn_mfma_f32_16x16x32_bf16(ka[p & 1][f * 4 + ks], bq[ks], a, 0, 0, 0);
;                 s[2 * p + f] = a; }
;             __builtin_amdgcn_sched_barrier(0);
;         }
;     ...
;     {
;         const LAS unsigned char* kl = lds + (q >> 2) * 2048 + (((q & 3) * 4 + g) ^ ((q >> 2) & 2)) * 16;
; #pragma unroll
;         for (int p = 0; p < 8; ++p)
; #pragma unroll
;             for (int f = 0; f < 2; ++f) { f32x4 a = {0.f, 0.f, 0.f, 0.f};
; #pragma unroll
;                 for (int ks = 0; ks < 4; ++ks) a = __builtin_amdgcn_mfma_f32_16x16x32_bf16(*(const LAS bf16x8*)(kl + p * 8192 + ks * 512 + f * 256), bq[ks], a, 0, 0, 0);
;                 s[2 * (CP + p) + f] = a; }
;     }
.Lring_k_B_nd15:
	ds_read_b128 v[18:21], v219 offset:0
	ds_read_b128 v[22:25], v219 offset:256
	ds_read_b128 v[26:29], v219 offset:512
	ds_read_b128 v[30:33], v219 offset:768
	s_waitcnt lgkmcnt(3)
	v_mfma_f32_16x16x32_bf16 v[78:81], v[18:21], v[130:133], v[78:81]
	s_waitcnt lgkmcnt(2)
	v_mfma_f32_16x16x32_bf16 v[74:77], v[22:25], v[130:133], v[74:77]
	s_waitcnt lgkmcnt(1)
	v_mfma_f32_16x16x32_bf16 v[78:81], v[26:29], v[62:65], v[78:81]
	s_waitcnt lgkmcnt(0)
	v_mfma_f32_16x16x32_bf16 v[74:77], v[30:33], v[62:65], v[74:77]
	s_cmp_eq_u32 s73, 0
	s_cbranch_scc1 .Lring_k_B_end
	s_waitcnt vmcnt(1)
	s_barrier
	ds_read_b128 v[2:5], v219 offset:8192
	ds_read_b128 v[6:9], v219 offset:8448
	ds_read_b128 v[10:13], v219 offset:8704
	ds_read_b128 v[14:17], v219 offset:8960
	s_waitcnt lgkmcnt(3)
	v_mfma_f32_16x16x32_bf16 v[70:73], v[2:5], v[138:141], 0
	s_waitcnt lgkmcnt(2)
	v_mfma_f32_16x16x32_bf16 v[66:69], v[6:9], v[138:141], 0
	s_waitcnt lgkmcnt(1)
	v_mfma_f32_16x16x32_bf16 v[70:73], v[10:13], v[134:137], v[70:73]
	s_waitcnt lgkmcnt(0)
	v_mfma_f32_16x16x32_bf16 v[66:69], v[14:17], v[134:137], v[66:69]
	s_waitcnt vmcnt(0)
	s_barrier
	ds_read_b128 v[18:21], v219 offset:16384
	ds_read_b128 v[22:25], v219 offset:16640
	ds_read_b128 v[26:29], v219 offset:16896
	ds_read_b128 v[30:33], v219 offset:17152
	s_waitcnt lgkmcnt(3)
	v_mfma_f32_16x16x32_bf16 v[70:73], v[18:21], v[130:133], v[70:73]
	s_waitcnt lgkmcnt(2)
	v_mfma_f32_16x16x32_bf16 v[66:69], v[22:25], v[130:133], v[66:69]
	s_waitcnt lgkmcnt(1)
	v_mfma_f32_16x16x32_bf16 v[70:73], v[26:29], v[62:65], v[70:73]
	s_waitcnt lgkmcnt(0)
	v_mfma_f32_16x16x32_bf16 v[66:69], v[30:33], v[62:65], v[66:69]
.Lring_k_B_end:
.Lring_k_done:
	s_nop 5
	s_waitcnt lgkmcnt(0)
	s_movk_i32 s4, 0x7c
	ds_read_b128 v[208:211], v169
	ds_read_b128 v[212:215], v169 offset:512
	ds_read_b128 v[216:219], v169 offset:1024
	ds_read_b128 v[220:223], v169 offset:1536
	ds_read_b128 v[224:227], v169 offset:256
	ds_read_b128 v[228:231], v169 offset:768
	ds_read_b128 v[232:235], v169 offset:1280
	ds_read_b128 v[246:249], v169 offset:1792
	s_waitcnt lgkmcnt(7)
	v_mfma_f32_16x16x32_bf16 v[2:5], v[208:211], v[138:141], 0
	ds_read_b128 v[208:211], v169 offset:8192
	s_waitcnt lgkmcnt(7)
	v_mfma_f32_16x16x32_bf16 v[2:5], v[212:215], v[134:137], v[2:5]
	ds_read_b128 v[212:215], v169 offset:8704
	s_waitcnt lgkmcnt(7)
	v_mfma_f32_16x16x32_bf16 v[2:5], v[216:219], v[130:133], v[2:5]
	ds_read_b128 v[216:219], v169 offset:9216
	s_waitcnt lgkmcnt(7)
	v_mfma_f32_16x16x32_bf16 v[2:5], v[220:223], v[62:65], v[2:5]
	ds_read_b128 v[220:223], v169 offset:9728
	s_waitcnt lgkmcnt(7)
	v_mfma_f32_16x16x32_bf16 v[6:9], v[224:227], v[138:141], 0
	ds_read_b128 v[224:227], v169 offset:8448
	s_waitcnt lgkmcnt(7)
	v_mfma_f32_16x16x32_bf16 v[6:9], v[228:231], v[134:137], v[6:9]
	ds_read_b128 v[228:231], v169 offset:8960
	s_waitcnt lgkmcnt(7)
	v_mfma_f32_16x16x32_bf16 v[6:9], v[232:235], v[130:133], v[6:9]
	ds_read_b128 v[232:235], v169 offset:9472
	s_waitcnt lgkmcnt(7)
	v_mfma_f32_16x16x32_bf16 v[10:13], v[246:249], v[62:65], v[6:9]
	ds_read_b128 v[246:249], v169 offset:9984
	s_waitcnt lgkmcnt(7)
	v_mfma_f32_16x16x32_bf16 v[6:9], v[208:211], v[138:141], 0
	ds_read_b128 v[208:211], v169 offset:16384
	s_waitcnt lgkmcnt(7)
	v_mfma_f32_16x16x32_bf16 v[6:9], v[212:215], v[134:137], v[6:9]
	ds_read_b128 v[212:215], v169 offset:16896
	s_waitcnt lgkmcnt(7)
	v_mfma_f32_16x16x32_bf16 v[6:9], v[216:219], v[130:133], v[6:9]
	ds_read_b128 v[216:219], v169 offset:17408
	s_waitcnt lgkmcnt(7)
	v_mfma_f32_16x16x32_bf16 v[6:9], v[220:223], v[62:65], v[6:9]
	ds_read_b128 v[220:223], v169 offset:17920
	s_waitcnt lgkmcnt(7)
	v_mfma_f32_16x16x32_bf16 v[14:17], v[224:227], v[138:141], 0
	ds_read_b128 v[224:227], v169 offset:16640
	s_waitcnt lgkmcnt(7)
	v_mfma_f32_16x16x32_bf16 v[14:17], v[228:231], v[134:137], v[14:17]
	ds_read_b128 v[228:231], v169 offset:17152
	s_waitcnt lgkmcnt(7)
	v_mfma_f32_16x16x32_bf16 v[14:17], v[232:235], v[130:133], v[14:17]
	ds_read_b128 v[232:235], v169 offset:17664
	s_waitcnt lgkmcnt(7)
	v_mfma_f32_16x16x32_bf16 v[18:21], v[246:249], v[62:65], v[14:17]
	ds_read_b128 v[246:249], v169 offset:18176
	s_waitcnt lgkmcnt(7)
	v_mfma_f32_16x16x32_bf16 v[14:17], v[208:211], v[138:141], 0
	ds_read_b128 v[208:211], v169 offset:24576
	s_waitcnt lgkmcnt(7)
	v_mfma_f32_16x16x32_bf16 v[14:17], v[212:215], v[134:137], v[14:17]
	ds_read_b128 v[212:215], v169 offset:25088
	s_waitcnt lgkmcnt(7)
	v_mfma_f32_16x16x32_bf16 v[14:17], v[216:219], v[130:133], v[14:17]
	ds_read_b128 v[216:219], v169 offset:25600
	s_waitcnt lgkmcnt(7)
	v_mfma_f32_16x16x32_bf16 v[14:17], v[220:223], v[62:65], v[14:17]
	ds_read_b128 v[220:223], v169 offset:26112
	s_waitcnt lgkmcnt(7)
	v_mfma_f32_16x16x32_bf16 v[22:25], v[224:227], v[138:141], 0
	ds_read_b128 v[224:227], v169 offset:24832
	s_waitcnt lgkmcnt(7)
	v_mfma_f32_16x16x32_bf16 v[22:25], v[228:231], v[134:137], v[22:25]
	ds_read_b128 v[228:231], v169 offset:25344
	s_waitcnt lgkmcnt(7)
	v_mfma_f32_16x16x32_bf16 v[22:25], v[232:235], v[130:133], v[22:25]
	ds_read_b128 v[232:235], v169 offset:25856
	s_waitcnt lgkmcnt(7)
	v_mfma_f32_16x16x32_bf16 v[26:29], v[246:249], v[62:65], v[22:25]
	ds_read_b128 v[246:249], v169 offset:26368
	s_waitcnt lgkmcnt(7)
; #define LAS __attribute__((address_space(3)))
; template <bool LOCAL>
; __device__ __forceinline__ void attn_unit(const bf16_t* Q, const bf16_t* KT, const bf16_t* VT, bf16_t* O, LAS unsigned char* lds, int b, int h, int r, int w, int tq, int lane) {
;     ...
;     {
;         const LAS unsigned char* kl = lds + (q >> 2) * 2048 + (((q & 3) * 4 + g) ^ ((q >> 2) & 2)) * 16;
; #pragma unroll
;         for (int p = 0; p < 8; ++p)
; #pragma unroll
;             for (int f = 0; f < 2; ++f) { f32x4 a = {0.f, 0.f, 0.f, 0.f};
; #pragma unroll
;                 for (int ks = 0; ks < 4; ++ks) a = __builtin_amdgcn_mfma_f32_16x16x32_bf16(*(const LAS bf16x8*)(kl + p * 8192 + ks * 512 + f * 256), bq[ks], a, 0, 0, 0);
;                 s[2 * (CP + p) + f] = a; }
;     }
;     if (LOCAL) {
;         const int c = 16 * w + q; int cs = c - 8; cs = cs < 0 ? 0 : (cs > 48 ? 48 : cs);
;         const LAS float* rp = (const LAS float*)(lds + LDS_MISC + 1024);
; #pragma unroll
;         for (int p = 0; p < 8; ++p) { const int ro = (rs + p - r + 7) * 31;
; #pragma unroll
;             for (int f = 0; f < 2; ++f)
; #pragma unroll
;                 for (int j = 0; j < 4; ++j) { const int kc = ws + 8 * g + 4 * f + j; const bool valid = (kc >= cs) && (kc < cs + 16);
;                     int rel = kc - c + 15; rel = rel < 0 ? 0 : (rel > 30 ? 30 : rel);
;                     const float bias = rp[ro + rel];
;                     s[p * 2 + f][j] = valid ? s[p * 2 + f][j] + bias : -INFINITY; } }
	v_mfma_f32_16x16x32_bf16 v[22:25], v[208:211], v[138:141], 0
	ds_read_b128 v[208:211], v169 offset:32768
	s_waitcnt lgkmcnt(7)
	v_mfma_f32_16x16x32_bf16 v[22:25], v[212:215], v[134:137], v[22:25]
	ds_read_b128 v[212:215], v169 offset:33280
	s_waitcnt lgkmcnt(7)
	v_mfma_f32_16x16x32_bf16 v[22:25], v[216:219], v[130:133], v[22:25]
	ds_read_b128 v[216:219], v169 offset:33792
	s_waitcnt lgkmcnt(7)
	v_mfma_f32_16x16x32_bf16 v[22:25], v[220:223], v[62:65], v[22:25]
	ds_read_b128 v[220:223], v169 offset:34304
	s_waitcnt lgkmcnt(7)
	v_mfma_f32_16x16x32_bf16 v[30:33], v[224:227], v[138:141], 0
	ds_read_b128 v[224:227], v169 offset:33024
	s_waitcnt lgkmcnt(7)
	v_mfma_f32_16x16x32_bf16 v[30:33], v[228:231], v[134:137], v[30:33]
	ds_read_b128 v[228:231], v169 offset:33536
	s_waitcnt lgkmcnt(7)
	v_mfma_f32_16x16x32_bf16 v[30:33], v[232:235], v[130:133], v[30:33]
	ds_read_b128 v[232:235], v169 offset:34048
	s_waitcnt lgkmcnt(7)
	v_mfma_f32_16x16x32_bf16 v[34:37], v[246:249], v[62:65], v[30:33]
	ds_read_b128 v[246:249], v169 offset:34560
	s_waitcnt lgkmcnt(7)
	v_mfma_f32_16x16x32_bf16 v[30:33], v[208:211], v[138:141], 0
	ds_read_b128 v[208:211], v169 offset:40960
	s_waitcnt lgkmcnt(7)
	v_mfma_f32_16x16x32_bf16 v[30:33], v[212:215], v[134:137], v[30:33]
	ds_read_b128 v[212:215], v169 offset:41472
	s_waitcnt lgkmcnt(7)
	v_mfma_f32_16x16x32_bf16 v[30:33], v[216:219], v[130:133], v[30:33]
	ds_read_b128 v[216:219], v169 offset:41984
	s_waitcnt lgkmcnt(7)
	v_mfma_f32_16x16x32_bf16 v[30:33], v[220:223], v[62:65], v[30:33]
	ds_read_b128 v[220:223], v169 offset:42496
	s_waitcnt lgkmcnt(7)
	v_mfma_f32_16x16x32_bf16 v[38:41], v[224:227], v[138:141], 0
	ds_read_b128 v[224:227], v169 offset:41216
	s_waitcnt lgkmcnt(7)
	v_mfma_f32_16x16x32_bf16 v[38:41], v[228:231], v[134:137], v[38:41]
	ds_read_b128 v[228:231], v169 offset:41728
	s_waitcnt lgkmcnt(7)
	v_mfma_f32_16x16x32_bf16 v[38:41], v[232:235], v[130:133], v[38:41]
	ds_read_b128 v[232:235], v169 offset:42240
	s_waitcnt lgkmcnt(7)
	v_mfma_f32_16x16x32_bf16 v[42:45], v[246:249], v[62:65], v[38:41]
	ds_read_b128 v[246:249], v169 offset:42752
	s_waitcnt lgkmcnt(7)
	v_mfma_f32_16x16x32_bf16 v[38:41], v[208:211], v[138:141], 0
	ds_read_b128 v[208:211], v169 offset:49152
	s_waitcnt lgkmcnt(7)
	v_mfma_f32_16x16x32_bf16 v[38:41], v[212:215], v[134:137], v[38:41]
	ds_read_b128 v[212:215], v169 offset:49664
	s_waitcnt lgkmcnt(7)
	v_mfma_f32_16x16x32_bf16 v[38:41], v[216:219], v[130:133], v[38:41]
	ds_read_b128 v[216:219], v169 offset:50176
	s_waitcnt lgkmcnt(7)
	v_mfma_f32_16x16x32_bf16 v[38:41], v[220:223], v[62:65], v[38:41]
	ds_read_b128 v[220:223], v169 offset:50688
	s_waitcnt lgkmcnt(7)
	v_mfma_f32_16x16x32_bf16 v[46:49], v[224:227], v[138:141], 0
	ds_read_b128 v[224:227], v169 offset:49408
	s_waitcnt lgkmcnt(7)
	v_mfma_f32_16x16x32_bf16 v[46:49], v[228:231], v[134:137], v[46:49]
	ds_read_b128 v[228:231], v169 offset:49920
	s_waitcnt lgkmcnt(7)
	v_mfma_f32_16x16x32_bf16 v[46:49], v[232:235], v[130:133], v[46:49]
	ds_read_b128 v[232:235], v169 offset:50432
	s_waitcnt lgkmcnt(7)
	v_mfma_f32_16x16x32_bf16 v[50:53], v[246:249], v[62:65], v[46:49]
	ds_read_b128 v[246:249], v169 offset:50944
	s_waitcnt lgkmcnt(7)
	v_mfma_f32_16x16x32_bf16 v[46:49], v[208:211], v[138:141], 0
	ds_read_b128 v[208:211], v169 offset:57344
	s_waitcnt lgkmcnt(7)
	v_mfma_f32_16x16x32_bf16 v[46:49], v[212:215], v[134:137], v[46:49]
	ds_read_b128 v[212:215], v169 offset:57856
	s_waitcnt lgkmcnt(7)
	v_mfma_f32_16x16x32_bf16 v[46:49], v[216:219], v[130:133], v[46:49]
	ds_read_b128 v[216:219], v169 offset:58368
	s_waitcnt lgkmcnt(7)
	v_mfma_f32_16x16x32_bf16 v[46:49], v[220:223], v[62:65], v[46:49]
	ds_read_b128 v[220:223], v169 offset:58880
	s_waitcnt lgkmcnt(7)
	v_mfma_f32_16x16x32_bf16 v[54:57], v[224:227], v[138:141], 0
	ds_read_b128 v[224:227], v169 offset:57600
	s_waitcnt lgkmcnt(7)
	v_mfma_f32_16x16x32_bf16 v[54:57], v[228:231], v[134:137], v[54:57]
	ds_read_b128 v[228:231], v169 offset:58112
	s_waitcnt lgkmcnt(7)
	v_mfma_f32_16x16x32_bf16 v[54:57], v[232:235], v[130:133], v[54:57]
	ds_read_b128 v[232:235], v169 offset:58624
	s_waitcnt lgkmcnt(7)
	v_mfma_f32_16x16x32_bf16 v[58:61], v[246:249], v[62:65], v[54:57]
	ds_read_b128 v[246:249], v169 offset:59136
	s_waitcnt lgkmcnt(7)
	v_mfma_f32_16x16x32_bf16 v[54:57], v[208:211], v[138:141], 0
	s_waitcnt lgkmcnt(6)
	v_mfma_f32_16x16x32_bf16 v[54:57], v[212:215], v[134:137], v[54:57]
	s_waitcnt lgkmcnt(5)
	v_mfma_f32_16x16x32_bf16 v[54:57], v[216:219], v[130:133], v[54:57]
	s_waitcnt lgkmcnt(4)
	v_mfma_f32_16x16x32_bf16 v[54:57], v[220:223], v[62:65], v[54:57]
	s_waitcnt lgkmcnt(3)
	v_mfma_f32_16x16x32_bf16 v[138:141], v[224:227], v[138:141], 0
	s_waitcnt lgkmcnt(2)
	v_mfma_f32_16x16x32_bf16 v[134:137], v[228:231], v[134:137], v[138:141]
	s_waitcnt lgkmcnt(1)
	v_mfma_f32_16x16x32_bf16 v[130:133], v[232:235], v[130:133], v[134:137]
	s_waitcnt lgkmcnt(0)
	v_mfma_f32_16x16x32_bf16 v[62:65], v[246:249], v[62:65], v[130:133]
	s_nop 7
	s_nop 2
	v_mul_lo_u32 v130, v195, s4
	v_add_u32_e32 v130, 0, v130
	v_add_u32_e32 v135, 0x20400, v130
	v_mov_b32_e32 v132, 0xff800000
	v_lshl_add_u32 v130, v170, 2, v135
	v_mov_b32_e32 v133, 0xff800000
	s_and_saveexec_b64 s[34:35], s[36:37]
	s_cbranch_execz .LBB9_676
	ds_read_b32 v131, v130 offset:928
	s_waitcnt lgkmcnt(0)
	v_add_f32_e32 v133, v126, v131

; #define LAS __attribute__((address_space(3)))
; __global__ void __launch_bounds__(NTHREADS, 2) mega(Args args) {
;     extern __shared__ __attribute__((aligned(16))) unsigned char lds_raw[];
;     LAS unsigned char* lds = (LAS unsigned char*)lds_raw;
	.amdhsa_kernel _Z4mega4Args
		.amdhsa_group_segment_fixed_size 16384
		.amdhsa_private_segment_fixed_size 0
		.amdhsa_kernarg_size 464
		.amdhsa_user_sgpr_count 2
		.amdhsa_user_sgpr_dispatch_ptr 0
		.amdhsa_user_sgpr_queue_ptr 0
		.amdhsa_user_sgpr_kernarg_segment_ptr 1
		.amdhsa_user_sgpr_dispatch_id 0
		.amdhsa_user_sgpr_kernarg_preload_length 0
		.amdhsa_user_sgpr_kernarg_preload_offset 0
		.amdhsa_user_sgpr_private_segment_size 0
		.amdhsa_uses_dynamic_stack 0
		.amdhsa_enable_private_segment 0
		.amdhsa_system_sgpr_workgroup_id_x 1
		.amdhsa_system_sgpr_workgroup_id_y 0
		.amdhsa_system_sgpr_workgroup_id_z 0
		.amdhsa_system_sgpr_workgroup_info 0
		.amdhsa_system_vgpr_workitem_id 0
		.amdhsa_next_free_vgpr 256
		.amdhsa_next_free_sgpr 100
		.amdhsa_accum_offset 256
		.amdhsa_reserve_vcc 1
		.amdhsa_float_round_mode_32 0
		.amdhsa_float_round_mode_16_64 0
		.amdhsa_float_denorm_mode_32 3
		.amdhsa_float_denorm_mode_16_64 3
		.amdhsa_dx10_clamp 1
		.amdhsa_ieee_mode 1
		.amdhsa_fp16_overflow 0
		.amdhsa_tg_split 0
		.amdhsa_exception_fp_ieee_invalid_op 0
		.amdhsa_exception_fp_denorm_src 0
		.amdhsa_exception_fp_ieee_div_zero 0
		.amdhsa_exception_fp_ieee_overflow 0
		.amdhsa_exception_fp_ieee_underflow 0
		.amdhsa_exception_fp_ieee_inexact 0
		.amdhsa_exception_int_div_zero 0
	.end_amdhsa_kernel

; __global__ void k_norm_mod(const float* X, const float* g, const float* mods_l, int sh_idx, float* H, int ldh) {
;     const int row = blockIdx.x, tid = threadIdx.x;
;     const float* xr = X + (size_t)row * D;
;     float v[8], ss = 0.f;
; #pragma unroll
;     for (int j = 0; j < 8; ++j) { v[j] = xr[tid + 256 * j]; ss += v[j] * v[j]; }
;     __shared__ float red[256];
;     red[tid] = ss; __syncthreads();
;     for (int o = 128; o > 0; o >>= 1) { if (tid < o) red[tid] += red[tid + o]; __syncthreads(); }
;     const float rstd = rsqrtf(red[0] / D + 1e-6f);
;     const int m = row_mod(row);
; #pragma unroll
;     for (int j = 0; j < 8; ++j) {
;         const int col = tid + 256 * j; float h = v[j] * rstd * g[col];
;         if (sh_idx >= 0) { const float sh = mods_l[(size_t)m * MODW + sh_idx * D + col], sc = mods_l[(size_t)m * MODW + (sh_idx + 1) * D + col]; h = h * (1.f + sc) + sh; }
;         H[(size_t)row * ldh + col] = h;
;     }
; }
; __global__ __launch_bounds__(256) void k_sgemm(const float* A, int lda, size_t sA, const float* B, int ldb, size_t sB, float* C, int ldc, size_t sC, int K) {
; __global__ void k_resid(float* X, const float* O, const float* mods_l, int g_idx, int rows) {
;     const size_t i = (size_t)blockIdx.x * 256 + threadIdx.x; if (i >= (size_t)rows * D) return;
;     const int row = i / D, col = i % D, m = row_mod(row);
;     X[i] += mods_l[(size_t)m * MODW + g_idx * D + col] * O[i];
; }
; __global__ void k_sqrelu(float* A, size_t n) { const size_t i = (size_t)blockIdx.x * 256 + threadIdx.x; if (i < n) { const float v = fmaxf(A[i], 0.f); A[i] = v * v; } }
; __global__ void k_conv(const float* GU, const float* cw, const float* cb, float* UC) {
;     const size_t i = (size_t)blockIdx.x * 256 + threadIdx.x; if (i >= (size_t)M * LW) return;
;     const int row = i / LW, c = i % LW;
;     int seg0, seglen; if (row < ML) { seg0 = (row / SEQ) * SEQ; seglen = SEQ; } else { seg0 = ML + ((row - ML) / CTX) * CTX; seglen = CTX; }
;     const int t = row - seg0; float s = cb[c];
;     for (int j = 0; j < 4; ++j) { const int tt = t + j - 2; if (tt >= 0 && tt < seglen) s += cw[j * LW + c] * GU[(size_t)(seg0 + tt) * (2 * LW) + LW + c]; }
;     UC[i] = s;
; }
amdhsa.kernels:
  - .agpr_count:     0
    .args:
      - .address_space:  global
        .offset:         0
        .size:           8
        .value_kind:     global_buffer
      - .address_space:  global
        .offset:         8
        .size:           8
        .value_kind:     global_buffer
      - .address_space:  global
        .offset:         16
        .size:           8
        .value_kind:     global_buffer
      - .offset:         24
        .size:           4
        .value_kind:     by_value
      - .address_space:  global
        .offset:         32
        .size:           8
        .value_kind:     global_buffer
      - .offset:         40
        .size:           4
        .value_kind:     by_value
    .group_segment_fixed_size: 1024
    .kernarg_segment_align: 8
    .kernarg_segment_size: 44
    .language:       OpenCL C
    .language_version:
      - 2
      - 0
    .max_flat_workgroup_size: 1024
    .name:           _ZN2nv10k_norm_modEPKfS1_S1_iPfi
    .private_segment_fixed_size: 0
    .sgpr_count:     20
    .sgpr_spill_count: 0
    .symbol:         _ZN2nv10k_norm_modEPKfS1_S1_iPfi.kd
    .uniform_work_group_size: 1
    .uses_dynamic_stack: false
    .vgpr_count:     18
    .vgpr_spill_count: 0
    .wavefront_size: 64
  - .agpr_count:     0
    .args:
      - .address_space:  global
        .offset:         0
        .size:           8
        .value_kind:     global_buffer
      - .offset:         8
        .size:           4
        .value_kind:     by_value
      - .offset:         16
        .size:           8
        .value_kind:     by_value
      - .address_space:  global
        .offset:         24
        .size:           8
        .value_kind:     global_buffer
      - .offset:         32
        .size:           4
        .value_kind:     by_value
      - .offset:         40
        .size:           8
        .value_kind:     by_value
      - .address_space:  global
        .offset:         48
        .size:           8
        .value_kind:     global_buffer
      - .offset:         56
        .size:           4
        .value_kind:     by_value
      - .offset:         64
        .size:           8
        .value_kind:     by_value
      - .offset:         72
        .size:           4
        .value_kind:     by_value
    .group_segment_fixed_size: 16896
    .kernarg_segment_align: 8
    .kernarg_segment_size: 76
    .language:       OpenCL C
    .language_version:
      - 2
      - 0
    .max_flat_workgroup_size: 256
    .name:           _ZN2nv7k_sgemmEPKfimS1_imPfimi
    .private_segment_fixed_size: 0
    .sgpr_count:     28
    .sgpr_spill_count: 0
    .symbol:         _ZN2nv7k_sgemmEPKfimS1_imPfimi.kd
    .uniform_work_group_size: 1
    .uses_dynamic_stack: false
    .vgpr_count:     138
    .vgpr_spill_count: 0
    .wavefront_size: 64
  - .agpr_count:     0
    .args:
      - .address_space:  global
        .offset:         0
        .size:           8
        .value_kind:     global_buffer
      - .address_space:  global
        .offset:         8
        .size:           8
        .value_kind:     global_buffer
      - .address_space:  global
        .offset:         16
        .size:           8
        .value_kind:     global_buffer
      - .offset:         24
        .size:           4
        .value_kind:     by_value
      - .offset:         28
        .size:           4
        .value_kind:     by_value
    .group_segment_fixed_size: 0
    .kernarg_segment_align: 8
    .kernarg_segment_size: 32
    .language:       OpenCL C
    .language_version:
      - 2
      - 0
    .max_flat_workgroup_size: 1024
    .name:           _ZN2nv7k_residEPfPKfS2_ii
    .private_segment_fixed_size: 0
    .sgpr_count:     18
    .sgpr_spill_count: 0
    .symbol:         _ZN2nv7k_residEPfPKfS2_ii.kd
    .uniform_work_group_size: 1
    .uses_dynamic_stack: false
    .vgpr_count:     7
    .vgpr_spill_count: 0
    .wavefront_size: 64
  - .agpr_count:     0
    .args:
      - .address_space:  global
        .offset:         0
        .size:           8
        .value_kind:     global_buffer
      - .offset:         8
        .size:           8
        .value_kind:     by_value
    .group_segment_fixed_size: 0
    .kernarg_segment_align: 8
    .kernarg_segment_size: 16
    .language:       OpenCL C
    .language_version:
      - 2
      - 0
    .max_flat_workgroup_size: 1024
    .name:           _ZN2nv8k_sqreluEPfm
    .private_segment_fixed_size: 0
    .sgpr_count:     14
    .sgpr_spill_count: 0
    .symbol:         _ZN2nv8k_sqreluEPfm.kd
    .uniform_work_group_size: 1
    .uses_dynamic_stack: false
    .vgpr_count:     4
    .vgpr_spill_count: 0
    .wavefront_size: 64
  - .agpr_count:     0
    .args:
      - .address_space:  global
        .offset:         0
        .size:           8
        .value_kind:     global_buffer
      - .address_space:  global
        .offset:         8
        .size:           8
        .value_kind:     global_buffer
      - .address_space:  global
        .offset:         16
        .size:           8
        .value_kind:     global_buffer
      - .address_space:  global
        .offset:         24
        .size:           8
        .value_kind:     global_buffer
    .group_segment_fixed_size: 0
    .kernarg_segment_align: 8
    .kernarg_segment_size: 32
    .language:       OpenCL C
    .language_version:
      - 2
      - 0
    .max_flat_workgroup_size: 1024
    .name:           _ZN2nv6k_convEPKfS1_S1_Pf
    .private_segment_fixed_size: 0
    .sgpr_count:     18
    .sgpr_spill_count: 0
    .symbol:         _ZN2nv6k_convEPKfS1_S1_Pf.kd
    .uniform_work_group_size: 1
    .uses_dynamic_stack: false
    .vgpr_count:     12
    .vgpr_spill_count: 0
    .wavefront_size: 64
; #define LAS __attribute__((address_space(3)))
; __device__ __forceinline__ float sigmoidf_(float x) { return 1.f / (1.f + expf(-x)); }
; __device__ __forceinline__ float gelu_tanh(float x) { return 0.5f * x * (1.f + tanhf(0.7978845608028654f * (x + 0.044715f * x * x * x))); }
; __global__ void k_lru_coef(float* RA, float* RX, const float* UC, const float* ba, const float* bx, const float* lam) {
;     const size_t i = (size_t)blockIdx.x * 256 + threadIdx.x; if (i >= (size_t)M * LW) return;
;     const int c = i % LW;
;     const float r = sigmoidf_(RA[i] + ba[c]), ig = sigmoidf_(RX[i] + bx[c]);
;     const float sp = log1pf(expf(-lam[c]));
;     const float log_a = -8.f * r * sp;
;     RA[i] = expf(log_a);
;     RX[i] = sqrtf(-expm1f(2.f * log_a)) * (ig * UC[i]);
; }
; __global__ void k_scan_dir(const float* A, const float* Bc, float* Y, int dir) {
;     const int idx = blockIdx.x * 256 + threadIdx.x; if (idx >= BATCH * LW) return;
;     const int b = idx / LW, c = idx % LW;
;     float h = 0.f;
;     if (dir == 0) {
;         for (int t = 0; t < CTX; ++t) { const size_t o = (size_t)(ML + b * CTX + t) * LW + c; h = A[o] * h + Bc[o]; Y[o] = h; }
;         for (int t = 0; t < SEQ; ++t) { const size_t o = (size_t)(b * SEQ + t) * LW + c; h = A[o] * h + Bc[o]; Y[o] = h; }
;     } else {
;         for (int t = CTX - 1; t >= 0; --t) { const size_t o = (size_t)(ML + b * CTX + t) * LW + c; h = A[o] * h + Bc[o]; Y[o] += h; }
;         for (int t = SEQ - 1; t >= 0; --t) { const size_t o = (size_t)(b * SEQ + t) * LW + c; h = A[o] * h + Bc[o]; Y[o] += h; }
;     }
; }
; __global__ void k_gate_mul(const float* GU, const float* Y, float* Z) {
;     const size_t i = (size_t)blockIdx.x * 256 + threadIdx.x; if (i >= (size_t)M * LW) return;
;     const int row = i / LW, c = i % LW;
;     Z[i] = gelu_tanh(GU[(size_t)row * (2 * LW) + c]) * Y[i];
; }
; __global__ __launch_bounds__(256) void k_attn(const float* QKV, const float* rpb_l, float* O) {
; __global__ void __launch_bounds__(NTHREADS, 2) mega(Args args) {
;     extern __shared__ __attribute__((aligned(16))) unsigned char lds_raw[];
;     LAS unsigned char* lds = (LAS unsigned char*)lds_raw;
  - .agpr_count:     0
    .args:
      - .address_space:  global
        .offset:         0
        .size:           8
        .value_kind:     global_buffer
      - .address_space:  global
        .offset:         8
        .size:           8
        .value_kind:     global_buffer
      - .address_space:  global
        .offset:         16
        .size:           8
        .value_kind:     global_buffer
      - .address_space:  global
        .offset:         24
        .size:           8
        .value_kind:     global_buffer
      - .address_space:  global
        .offset:         32
        .size:           8
        .value_kind:     global_buffer
      - .address_space:  global
        .offset:         40
        .size:           8
        .value_kind:     global_buffer
    .group_segment_fixed_size: 0
    .kernarg_segment_align: 8
    .kernarg_segment_size: 48
    .language:       OpenCL C
    .language_version:
      - 2
      - 0
    .max_flat_workgroup_size: 1024
    .name:           _ZN2nv10k_lru_coefEPfS0_PKfS2_S2_S2_
    .private_segment_fixed_size: 0
    .sgpr_count:     22
    .sgpr_spill_count: 0
    .symbol:         _ZN2nv10k_lru_coefEPfS0_PKfS2_S2_S2_.kd
    .uniform_work_group_size: 1
    .uses_dynamic_stack: false
    .vgpr_count:     25
    .vgpr_spill_count: 0
    .wavefront_size: 64
  - .agpr_count:     0
    .args:
      - .address_space:  global
        .offset:         0
        .size:           8
        .value_kind:     global_buffer
      - .address_space:  global
        .offset:         8
        .size:           8
        .value_kind:     global_buffer
      - .address_space:  global
        .offset:         16
        .size:           8
        .value_kind:     global_buffer
      - .offset:         24
        .size:           4
        .value_kind:     by_value
    .group_segment_fixed_size: 0
    .kernarg_segment_align: 8
    .kernarg_segment_size: 28
    .language:       OpenCL C
    .language_version:
      - 2
      - 0
    .max_flat_workgroup_size: 1024
    .name:           _ZN2nv10k_scan_dirEPKfS1_Pfi
    .private_segment_fixed_size: 0
    .sgpr_count:     23
    .sgpr_spill_count: 0
    .symbol:         _ZN2nv10k_scan_dirEPKfS1_Pfi.kd
    .uniform_work_group_size: 1
    .uses_dynamic_stack: false
    .vgpr_count:     36
    .vgpr_spill_count: 0
    .wavefront_size: 64
  - .agpr_count:     0
    .args:
      - .address_space:  global
        .offset:         0
        .size:           8
        .value_kind:     global_buffer
      - .address_space:  global
        .offset:         8
        .size:           8
        .value_kind:     global_buffer
      - .address_space:  global
        .offset:         16
        .size:           8
        .value_kind:     global_buffer
    .group_segment_fixed_size: 0
    .kernarg_segment_align: 8
    .kernarg_segment_size: 24
    .language:       OpenCL C
    .language_version:
      - 2
      - 0
    .max_flat_workgroup_size: 1024
    .name:           _ZN2nv10k_gate_mulEPKfS1_Pf
    .private_segment_fixed_size: 0
    .sgpr_count:     14
    .sgpr_spill_count: 0
    .symbol:         _ZN2nv10k_gate_mulEPKfS1_Pf.kd
    .uniform_work_group_size: 1
    .uses_dynamic_stack: false
    .vgpr_count:     8
    .vgpr_spill_count: 0
    .wavefront_size: 64
  - .agpr_count:     8
    .args:
      - .address_space:  global
        .offset:         0
        .size:           8
        .value_kind:     global_buffer
      - .address_space:  global
        .offset:         8
        .size:           8
        .value_kind:     global_buffer
      - .address_space:  global
        .offset:         16
        .size:           8
        .value_kind:     global_buffer
    .group_segment_fixed_size: 8192
    .kernarg_segment_align: 8
    .kernarg_segment_size: 24
    .language:       OpenCL C
    .language_version:
      - 2
      - 0
    .max_flat_workgroup_size: 256
    .name:           _ZN2nv6k_attnEPKfS1_Pf
    .private_segment_fixed_size: 0
    .sgpr_count:     23
    .sgpr_spill_count: 0
    .symbol:         _ZN2nv6k_attnEPKfS1_Pf.kd
    .uniform_work_group_size: 1
    .uses_dynamic_stack: false
    .vgpr_count:     264
    .vgpr_spill_count: 0
    .wavefront_size: 64
  - .agpr_count:     0
    .args:
      - .offset:         0
        .size:           208
        .value_kind:     by_value
      - .offset:         208
        .size:           4
        .value_kind:     hidden_block_count_x
      - .offset:         212
        .size:           4
        .value_kind:     hidden_block_count_y
      - .offset:         216
        .size:           4
        .value_kind:     hidden_block_count_z
      - .offset:         220
        .size:           2
        .value_kind:     hidden_group_size_x
      - .offset:         222
        .size:           2
        .value_kind:     hidden_group_size_y
      - .offset:         224
        .size:           2
        .value_kind:     hidden_group_size_z
      - .offset:         226
        .size:           2
        .value_kind:     hidden_remainder_x
      - .offset:         228
        .size:           2
        .value_kind:     hidden_remainder_y
      - .offset:         230
        .size:           2
        .value_kind:     hidden_remainder_z
      - .offset:         248
        .size:           8
        .value_kind:     hidden_global_offset_x
      - .offset:         256
        .size:           8
        .value_kind:     hidden_global_offset_y
      - .offset:         264
        .size:           8
        .value_kind:     hidden_global_offset_z
      - .offset:         272
        .size:           2
        .value_kind:     hidden_grid_dims
      - .offset:         328
        .size:           4
        .value_kind:     hidden_dynamic_lds_size
    .group_segment_fixed_size: 16384
    .kernarg_segment_align: 8
    .kernarg_segment_size: 464
    .language:       OpenCL C
    .language_version:
      - 2
      - 0
    .max_flat_workgroup_size: 512
    .name:           _Z4mega4Args
    .private_segment_fixed_size: 0
    .sgpr_count:     106
    .sgpr_spill_count: 136
    .symbol:         _Z4mega4Args.kd
    .uniform_work_group_size: 1
    .uses_dynamic_stack: false
    .vgpr_count:     256
    .vgpr_spill_count: 0
    .wavefront_size: 64
